# v34 + nt cache policy on the FFN-up epilogues' fp8 activation stores (streaming output, consumed by the next phase from beyond L2)
# baseline (speedup 1.0000x reference)
;     __device__ __forceinline__ void operator()(const f32x4 (&acc)[2][2][4][2], const pg8::Unit& u, int wr, int wc, int fr, int fq) const {
;         const int row0 = u.pm * 256 + wr * 64 + fr, col0 = u.pn * 128 + wc * 32 + 8 * fq;
; #pragma unroll
;         for (int ai = 0; ai < 2; ++ai)
; #pragma unroll
;             for (int m = 0; m < 4; ++m) {
;                 unsigned char* rowp = O + (size_t)(row0 + ai * 128 + m * 16) * DFF + col0;
;                 float v[8];
; #pragma unroll
;                 for (int n = 0; n < 2; ++n)
; #pragma unroll
;                     for (int j = 0; j < 4; ++j) { const float g = acc[ai][0][m][n][j], up = acc[ai][1][m][n][j]; v[4 * n + j] = g * up * __builtin_amdgcn_rcpf(__builtin_fmaf(__builtin_amdgcn_exp2f(-1.44269504089f * g), 1.0f / ACT8_SCALE, 1.0f / ACT8_SCALE)); }
;                 u32x2 w; w.x = pk4_fp8(v[0], v[1], v[2], v[3]); w.y = pk4_fp8(v[4], v[5], v[6], v[7]);
;                 *(u32x2*)rowp = w;
.LBB0_222:
	v_mul_f32_e32 v150, 0xbfb8aa3b, v126
	v_exp_f32_e32 v160, v150
	v_mul_f32_e32 v150, 0xbfb8aa3b, v127
	v_mul_f32_e32 v122, v126, v122
	v_mul_f32_e32 v123, v127, v123
	v_mul_f32_e32 v126, 0xbfb8aa3b, v128
	v_mul_f32_e32 v127, 0xbfb8aa3b, v129
	v_exp_f32_e32 v126, v126
	v_exp_f32_e32 v127, v127
	v_mul_f32_e32 v124, v128, v124
	v_mul_f32_e32 v128, 0xbfb8aa3b, v118
	v_fmamk_f32 v126, v126, 0x3e000000, v157
	v_fmamk_f32 v127, v127, 0x3e000000, v157
	v_rcp_f32_e32 v126, v126
	v_rcp_f32_e32 v127, v127
	v_exp_f32_e32 v128, v128
	v_mul_f32_e32 v125, v129, v125
	v_mul_f32_e32 v124, v126, v124
	v_mul_f32_e32 v125, v127, v125
	v_fmamk_f32 v126, v128, 0x3e000000, v157
	v_mul_f32_e32 v127, 0xbfb8aa3b, v119
	v_rcp_f32_e32 v126, v126
	v_exp_f32_e32 v127, v127
	v_mul_f32_e32 v114, v118, v114
	v_exp_f32_e32 v161, v150
	v_mul_f32_e32 v118, v126, v114
	v_mul_f32_e32 v114, v119, v115
	v_fmamk_f32 v115, v127, 0x3e000000, v157
	v_mul_f32_e32 v119, 0xbfb8aa3b, v120
	v_rcp_f32_e32 v115, v115
	v_exp_f32_e32 v119, v119
	v_mul_f32_e32 v126, 0xbfb8aa3b, v121
	v_exp_f32_e32 v126, v126
	v_fmamk_f32 v160, v160, 0x3e000000, v157
	v_fmamk_f32 v161, v161, 0x3e000000, v157
	v_mul_f32_e32 v115, v115, v114
	v_fmamk_f32 v114, v119, 0x3e000000, v157
	v_rcp_f32_e32 v160, v160
	v_rcp_f32_e32 v161, v161
	v_rcp_f32_e32 v114, v114
	v_fmamk_f32 v119, v126, 0x3e000000, v157
	v_rcp_f32_e32 v119, v119
	v_mul_f32_e32 v116, v120, v116
	v_mul_f32_e32 v122, v160, v122
	v_mul_f32_e32 v123, v161, v123
	v_mul_f32_e32 v116, v114, v116
	v_mul_f32_e32 v114, v121, v117
	v_mul_f32_e32 v117, v119, v114
	v_med3_f32 v119, v122, s42, v158
	v_med3_f32 v120, v123, s42, v158
	v_mov_b32_e32 v114, 0
	v_med3_f32 v118, v118, s42, v158
	v_med3_f32 v121, v115, s42, v158
	v_mov_b32_e32 v115, 0
	v_cvt_pk_fp8_f32 v114, v119, v120
	v_cvt_pk_fp8_f32 v115, v118, v121
	v_readlane_b32 s20, v253, 50
	v_med3_f32 v119, v124, s42, v158
	v_med3_f32 v120, v125, s42, v158
	v_med3_f32 v116, v116, s42, v158
	v_med3_f32 v117, v117, s42, v158
	v_readlane_b32 s21, v253, 51
	v_cvt_pk_fp8_f32 v114, v119, v120 op_sel:[0,0,1]
	v_cvt_pk_fp8_f32 v115, v116, v117 op_sel:[0,0,1]
	v_lshl_add_u32 v159, s18, 8, v131
	v_lshl_or_b32 v148, s43, 7, v153
	v_mov_b64_e32 v[150:151], s[20:21]
	v_ashrrev_i32_e32 v149, 31, v148
	v_mad_i64_i32 v[116:117], s[20:21], v159, s41, v[150:151]
	v_lshl_add_u64 v[116:117], v[116:117], 0, v[148:149]
	global_store_dwordx2 v[116:117], v[114:115], off nt
	v_mul_f32_e32 v114, 0xbfb8aa3b, v110
	v_mul_f32_e32 v115, 0xbfb8aa3b, v111
	v_mul_f32_e32 v106, v110, v106
	v_mul_f32_e32 v107, v111, v107
	v_mul_f32_e32 v110, 0xbfb8aa3b, v112
	v_mul_f32_e32 v111, 0xbfb8aa3b, v113
	v_exp_f32_e32 v110, v110
	v_exp_f32_e32 v111, v111
	v_mul_f32_e32 v108, v112, v108
	v_mul_f32_e32 v112, 0xbfb8aa3b, v102
	v_fmamk_f32 v110, v110, 0x3e000000, v157
	v_fmamk_f32 v111, v111, 0x3e000000, v157
	v_rcp_f32_e32 v110, v110
	v_rcp_f32_e32 v111, v111
	v_exp_f32_e32 v112, v112
	v_mul_f32_e32 v109, v113, v109
	v_mul_f32_e32 v108, v110, v108
	v_mul_f32_e32 v109, v111, v109
	v_fmamk_f32 v110, v112, 0x3e000000, v157
	v_mul_f32_e32 v111, 0xbfb8aa3b, v103
	v_rcp_f32_e32 v110, v110
	v_exp_f32_e32 v111, v111
	v_mul_f32_e32 v98, v102, v98
	v_exp_f32_e32 v114, v114
	v_mul_f32_e32 v102, v110, v98
	v_mul_f32_e32 v98, v103, v99
	v_fmamk_f32 v99, v111, 0x3e000000, v157
	v_mul_f32_e32 v103, 0xbfb8aa3b, v104
	v_exp_f32_e32 v115, v115
	v_rcp_f32_e32 v99, v99
	v_exp_f32_e32 v103, v103
	v_mul_f32_e32 v110, 0xbfb8aa3b, v105
	v_exp_f32_e32 v110, v110
	v_fmamk_f32 v114, v114, 0x3e000000, v157
	v_fmamk_f32 v115, v115, 0x3e000000, v157
	v_mul_f32_e32 v99, v99, v98
	v_fmamk_f32 v98, v103, 0x3e000000, v157
	v_rcp_f32_e32 v114, v114
	v_rcp_f32_e32 v115, v115
	v_rcp_f32_e32 v98, v98
	v_fmamk_f32 v103, v110, 0x3e000000, v157
	v_rcp_f32_e32 v103, v103
	v_mul_f32_e32 v100, v104, v100
	v_mul_f32_e32 v106, v114, v106
	v_mul_f32_e32 v107, v115, v107
	v_mul_f32_e32 v100, v98, v100
	v_mul_f32_e32 v98, v105, v101
	v_mul_f32_e32 v101, v103, v98
	v_med3_f32 v103, v106, s42, v158
	v_med3_f32 v104, v107, s42, v158
	v_mov_b32_e32 v98, 0
	v_med3_f32 v102, v102, s42, v158
	v_med3_f32 v105, v99, s42, v158
	v_mov_b32_e32 v99, 0
	v_cvt_pk_fp8_f32 v98, v103, v104
	v_cvt_pk_fp8_f32 v99, v102, v105
	v_med3_f32 v103, v108, s42, v158
	v_med3_f32 v104, v109, s42, v158
	v_med3_f32 v100, v100, s42, v158
	v_med3_f32 v101, v101, s42, v158
	v_cvt_pk_fp8_f32 v98, v103, v104 op_sel:[0,0,1]
	v_cvt_pk_fp8_f32 v99, v100, v101 op_sel:[0,0,1]
	v_or_b32_e32 v116, 16, v159
	v_mad_i64_i32 v[100:101], s[20:21], v116, s41, v[150:151]
	v_lshl_add_u64 v[100:101], v[100:101], 0, v[148:149]
	global_store_dwordx2 v[100:101], v[98:99], off nt
	v_mul_f32_e32 v98, 0xbfb8aa3b, v94
	v_mul_f32_e32 v99, 0xbfb8aa3b, v95
	v_mul_f32_e32 v90, v94, v90
	v_mul_f32_e32 v91, v95, v91
	v_mul_f32_e32 v94, 0xbfb8aa3b, v96
	v_mul_f32_e32 v95, 0xbfb8aa3b, v97
	v_exp_f32_e32 v94, v94
	v_exp_f32_e32 v95, v95
	v_mul_f32_e32 v92, v96, v92
	v_mul_f32_e32 v96, 0xbfb8aa3b, v86
	v_fmamk_f32 v94, v94, 0x3e000000, v157
	v_fmamk_f32 v95, v95, 0x3e000000, v157
	v_rcp_f32_e32 v94, v94
	v_rcp_f32_e32 v95, v95
	v_exp_f32_e32 v96, v96
	v_mul_f32_e32 v93, v97, v93
	v_mul_f32_e32 v92, v94, v92
	v_mul_f32_e32 v93, v95, v93
	v_fmamk_f32 v94, v96, 0x3e000000, v157
	v_mul_f32_e32 v95, 0xbfb8aa3b, v87
	v_rcp_f32_e32 v94, v94
	v_exp_f32_e32 v95, v95
	v_mul_f32_e32 v82, v86, v82
	v_exp_f32_e32 v98, v98
	v_mul_f32_e32 v86, v94, v82
	v_mul_f32_e32 v82, v87, v83
	v_fmamk_f32 v83, v95, 0x3e000000, v157
	v_mul_f32_e32 v87, 0xbfb8aa3b, v88
	v_exp_f32_e32 v99, v99
	v_rcp_f32_e32 v83, v83
	v_exp_f32_e32 v87, v87
	v_mul_f32_e32 v94, 0xbfb8aa3b, v89
;     __device__ __forceinline__ void operator()(const f32x4 (&acc)[2][2][4][2], const pg8::Unit& u, int wr, int wc, int fr, int fq) const {
;     ...
;             for (int m = 0; m < 4; ++m) {
;                 unsigned char* rowp = O + (size_t)(row0 + ai * 128 + m * 16) * DFF + col0;
;                 float v[8];
; #pragma unroll
;                 for (int n = 0; n < 2; ++n)
; #pragma unroll
;                     for (int j = 0; j < 4; ++j) { const float g = acc[ai][0][m][n][j], up = acc[ai][1][m][n][j]; v[4 * n + j] = g * up * __builtin_amdgcn_rcpf(__builtin_fmaf(__builtin_amdgcn_exp2f(-1.44269504089f * g), 1.0f / ACT8_SCALE, 1.0f / ACT8_SCALE)); }
;                 u32x2 w; w.x = pk4_fp8(v[0], v[1], v[2], v[3]); w.y = pk4_fp8(v[4], v[5], v[6], v[7]);
;                 *(u32x2*)rowp = w;
	v_exp_f32_e32 v94, v94
	v_fmamk_f32 v98, v98, 0x3e000000, v157
	v_fmamk_f32 v99, v99, 0x3e000000, v157
	v_mul_f32_e32 v83, v83, v82
	v_fmamk_f32 v82, v87, 0x3e000000, v157
	v_rcp_f32_e32 v98, v98
	v_rcp_f32_e32 v99, v99
	v_rcp_f32_e32 v82, v82
	v_fmamk_f32 v87, v94, 0x3e000000, v157
	v_rcp_f32_e32 v87, v87
	v_mul_f32_e32 v84, v88, v84
	v_mul_f32_e32 v90, v98, v90
	v_mul_f32_e32 v91, v99, v91
	v_mul_f32_e32 v84, v82, v84
	v_mul_f32_e32 v82, v89, v85
	v_mul_f32_e32 v85, v87, v82
	v_med3_f32 v87, v90, s42, v158
	v_med3_f32 v88, v91, s42, v158
	v_mov_b32_e32 v82, 0
	v_med3_f32 v86, v86, s42, v158
	v_med3_f32 v89, v83, s42, v158
	v_mov_b32_e32 v83, 0
	v_cvt_pk_fp8_f32 v82, v87, v88
	v_cvt_pk_fp8_f32 v83, v86, v89
	v_med3_f32 v87, v92, s42, v158
	v_med3_f32 v88, v93, s42, v158
	v_med3_f32 v84, v84, s42, v158
	v_med3_f32 v85, v85, s42, v158
	v_cvt_pk_fp8_f32 v82, v87, v88 op_sel:[0,0,1]
	v_cvt_pk_fp8_f32 v83, v84, v85 op_sel:[0,0,1]
	v_or_b32_e32 v100, 32, v159
	v_mad_i64_i32 v[84:85], s[20:21], v100, s41, v[150:151]
	v_lshl_add_u64 v[84:85], v[84:85], 0, v[148:149]
	global_store_dwordx2 v[84:85], v[82:83], off nt
	v_mul_f32_e32 v82, 0xbfb8aa3b, v78
	v_mul_f32_e32 v83, 0xbfb8aa3b, v79
	v_mul_f32_e32 v74, v78, v74
	v_mul_f32_e32 v75, v79, v75
	v_mul_f32_e32 v78, 0xbfb8aa3b, v80
	v_mul_f32_e32 v79, 0xbfb8aa3b, v81
	v_exp_f32_e32 v78, v78
	v_exp_f32_e32 v79, v79
	v_mul_f32_e32 v76, v80, v76
	v_mul_f32_e32 v80, 0xbfb8aa3b, v70
	v_fmamk_f32 v78, v78, 0x3e000000, v157
	v_fmamk_f32 v79, v79, 0x3e000000, v157
	v_rcp_f32_e32 v78, v78
	v_rcp_f32_e32 v79, v79
	v_exp_f32_e32 v80, v80
	v_mul_f32_e32 v77, v81, v77
	v_mul_f32_e32 v76, v78, v76
	v_mul_f32_e32 v77, v79, v77
	v_fmamk_f32 v78, v80, 0x3e000000, v157
	v_mul_f32_e32 v79, 0xbfb8aa3b, v71
	v_rcp_f32_e32 v78, v78
	v_exp_f32_e32 v79, v79
	v_mul_f32_e32 v66, v70, v66
	v_exp_f32_e32 v82, v82
	v_mul_f32_e32 v70, v78, v66
	v_mul_f32_e32 v66, v71, v67
	v_fmamk_f32 v67, v79, 0x3e000000, v157
	v_mul_f32_e32 v71, 0xbfb8aa3b, v72
	v_exp_f32_e32 v83, v83
	v_rcp_f32_e32 v67, v67
	v_exp_f32_e32 v71, v71
	v_mul_f32_e32 v78, 0xbfb8aa3b, v73
	v_exp_f32_e32 v78, v78
	v_fmamk_f32 v82, v82, 0x3e000000, v157
	v_fmamk_f32 v83, v83, 0x3e000000, v157
	v_mul_f32_e32 v67, v67, v66
	v_fmamk_f32 v66, v71, 0x3e000000, v157
	v_rcp_f32_e32 v82, v82
	v_rcp_f32_e32 v83, v83
	v_rcp_f32_e32 v66, v66
	v_fmamk_f32 v71, v78, 0x3e000000, v157
	v_rcp_f32_e32 v71, v71
	v_mul_f32_e32 v68, v72, v68
	v_mul_f32_e32 v74, v82, v74
	v_mul_f32_e32 v75, v83, v75
	v_mul_f32_e32 v68, v66, v68
	v_mul_f32_e32 v66, v73, v69
	v_mul_f32_e32 v69, v71, v66
	v_med3_f32 v71, v74, s42, v158
	v_med3_f32 v72, v75, s42, v158
	v_mov_b32_e32 v66, 0
	v_med3_f32 v70, v70, s42, v158
	v_med3_f32 v73, v67, s42, v158
	v_mov_b32_e32 v67, 0
	v_cvt_pk_fp8_f32 v66, v71, v72
	v_cvt_pk_fp8_f32 v67, v70, v73
	v_med3_f32 v71, v76, s42, v158
	v_med3_f32 v72, v77, s42, v158
	v_med3_f32 v68, v68, s42, v158
	v_med3_f32 v69, v69, s42, v158
	v_cvt_pk_fp8_f32 v66, v71, v72 op_sel:[0,0,1]
	v_cvt_pk_fp8_f32 v67, v68, v69 op_sel:[0,0,1]
	v_or_b32_e32 v84, 48, v159
	v_mad_i64_i32 v[68:69], s[20:21], v84, s41, v[150:151]
	v_lshl_add_u64 v[68:69], v[68:69], 0, v[148:149]
	global_store_dwordx2 v[68:69], v[66:67], off nt
	v_mul_f32_e32 v66, 0xbfb8aa3b, v62
	v_mul_f32_e32 v67, 0xbfb8aa3b, v63
	v_mul_f32_e32 v58, v62, v58
	v_mul_f32_e32 v59, v63, v59
	v_mul_f32_e32 v62, 0xbfb8aa3b, v64
	v_mul_f32_e32 v63, 0xbfb8aa3b, v65
	v_exp_f32_e32 v62, v62
	v_exp_f32_e32 v63, v63
	v_mul_f32_e32 v60, v64, v60
	v_mul_f32_e32 v64, 0xbfb8aa3b, v54
	v_fmamk_f32 v62, v62, 0x3e000000, v157
	v_fmamk_f32 v63, v63, 0x3e000000, v157
	v_rcp_f32_e32 v62, v62
	v_rcp_f32_e32 v63, v63
	v_exp_f32_e32 v64, v64
	v_mul_f32_e32 v61, v65, v61
	v_mul_f32_e32 v60, v62, v60
	v_mul_f32_e32 v61, v63, v61
	v_fmamk_f32 v62, v64, 0x3e000000, v157
	v_mul_f32_e32 v63, 0xbfb8aa3b, v55
	v_rcp_f32_e32 v62, v62
	v_exp_f32_e32 v63, v63
	v_mul_f32_e32 v50, v54, v50
	v_exp_f32_e32 v66, v66
	v_mul_f32_e32 v54, v62, v50
	v_mul_f32_e32 v50, v55, v51
	v_fmamk_f32 v51, v63, 0x3e000000, v157
	v_mul_f32_e32 v55, 0xbfb8aa3b, v56
	v_exp_f32_e32 v67, v67
	v_rcp_f32_e32 v51, v51
	v_exp_f32_e32 v55, v55
	v_mul_f32_e32 v62, 0xbfb8aa3b, v57
	v_exp_f32_e32 v62, v62
	v_fmamk_f32 v66, v66, 0x3e000000, v157
	v_fmamk_f32 v67, v67, 0x3e000000, v157
	v_mul_f32_e32 v51, v51, v50
	v_fmamk_f32 v50, v55, 0x3e000000, v157
	v_rcp_f32_e32 v66, v66
	v_rcp_f32_e32 v67, v67
	v_rcp_f32_e32 v50, v50
	v_fmamk_f32 v55, v62, 0x3e000000, v157
	v_rcp_f32_e32 v55, v55
	v_mul_f32_e32 v52, v56, v52
	v_mul_f32_e32 v58, v66, v58
	v_mul_f32_e32 v59, v67, v59
	v_mul_f32_e32 v52, v50, v52
	v_mul_f32_e32 v50, v57, v53
	v_mul_f32_e32 v53, v55, v50
	v_med3_f32 v55, v58, s42, v158
	v_med3_f32 v56, v59, s42, v158
	v_mov_b32_e32 v50, 0
	v_med3_f32 v54, v54, s42, v158
	v_med3_f32 v57, v51, s42, v158
	v_mov_b32_e32 v51, 0
	v_cvt_pk_fp8_f32 v50, v55, v56
	v_cvt_pk_fp8_f32 v51, v54, v57
	v_med3_f32 v55, v60, s42, v158
	v_med3_f32 v56, v61, s42, v158
	v_med3_f32 v52, v52, s42, v158
	v_med3_f32 v53, v53, s42, v158
	v_cvt_pk_fp8_f32 v50, v55, v56 op_sel:[0,0,1]
	v_cvt_pk_fp8_f32 v51, v52, v53 op_sel:[0,0,1]
	v_add_u32_e32 v68, 0x80, v159
	v_mad_i64_i32 v[52:53], s[20:21], v68, s41, v[150:151]
	v_lshl_add_u64 v[52:53], v[52:53], 0, v[148:149]
	global_store_dwordx2 v[52:53], v[50:51], off nt
	v_mul_f32_e32 v50, 0xbfb8aa3b, v46
	v_mul_f32_e32 v51, 0xbfb8aa3b, v47
	v_mul_f32_e32 v42, v46, v42
	v_mul_f32_e32 v43, v47, v43
	v_mul_f32_e32 v46, 0xbfb8aa3b, v48
	v_mul_f32_e32 v47, 0xbfb8aa3b, v49
	v_exp_f32_e32 v46, v46
	v_exp_f32_e32 v47, v47
	v_mul_f32_e32 v44, v48, v44
	v_mul_f32_e32 v48, 0xbfb8aa3b, v38
;     __device__ __forceinline__ void operator()(const f32x4 (&acc)[2][2][4][2], const pg8::Unit& u, int wr, int wc, int fr, int fq) const {
;     ...
;             for (int m = 0; m < 4; ++m) {
;                 unsigned char* rowp = O + (size_t)(row0 + ai * 128 + m * 16) * DFF + col0;
;                 float v[8];
; #pragma unroll
;                 for (int n = 0; n < 2; ++n)
; #pragma unroll
;                     for (int j = 0; j < 4; ++j) { const float g = acc[ai][0][m][n][j], up = acc[ai][1][m][n][j]; v[4 * n + j] = g * up * __builtin_amdgcn_rcpf(__builtin_fmaf(__builtin_amdgcn_exp2f(-1.44269504089f * g), 1.0f / ACT8_SCALE, 1.0f / ACT8_SCALE)); }
;                 u32x2 w; w.x = pk4_fp8(v[0], v[1], v[2], v[3]); w.y = pk4_fp8(v[4], v[5], v[6], v[7]);
;                 *(u32x2*)rowp = w;
	v_fmamk_f32 v46, v46, 0x3e000000, v157
	v_fmamk_f32 v47, v47, 0x3e000000, v157
	v_rcp_f32_e32 v46, v46
	v_rcp_f32_e32 v47, v47
	v_exp_f32_e32 v48, v48
	v_mul_f32_e32 v45, v49, v45
	v_mul_f32_e32 v44, v46, v44
	v_mul_f32_e32 v45, v47, v45
	v_fmamk_f32 v46, v48, 0x3e000000, v157
	v_mul_f32_e32 v47, 0xbfb8aa3b, v39
	v_rcp_f32_e32 v46, v46
	v_exp_f32_e32 v47, v47
	v_mul_f32_e32 v34, v38, v34
	v_exp_f32_e32 v50, v50
	v_mul_f32_e32 v38, v46, v34
	v_mul_f32_e32 v34, v39, v35
	v_fmamk_f32 v35, v47, 0x3e000000, v157
	v_mul_f32_e32 v39, 0xbfb8aa3b, v40
	v_exp_f32_e32 v51, v51
	v_rcp_f32_e32 v35, v35
	v_exp_f32_e32 v39, v39
	v_mul_f32_e32 v46, 0xbfb8aa3b, v41
	v_exp_f32_e32 v46, v46
	v_fmamk_f32 v50, v50, 0x3e000000, v157
	v_fmamk_f32 v51, v51, 0x3e000000, v157
	v_mul_f32_e32 v35, v35, v34
	v_fmamk_f32 v34, v39, 0x3e000000, v157
	v_rcp_f32_e32 v50, v50
	v_rcp_f32_e32 v51, v51
	v_rcp_f32_e32 v34, v34
	v_fmamk_f32 v39, v46, 0x3e000000, v157
	v_rcp_f32_e32 v39, v39
	v_mul_f32_e32 v36, v40, v36
	v_mul_f32_e32 v42, v50, v42
	v_mul_f32_e32 v43, v51, v43
	v_mul_f32_e32 v36, v34, v36
	v_mul_f32_e32 v34, v41, v37
	v_mul_f32_e32 v37, v39, v34
	v_med3_f32 v39, v42, s42, v158
	v_med3_f32 v40, v43, s42, v158
	v_mov_b32_e32 v34, 0
	v_med3_f32 v38, v38, s42, v158
	v_med3_f32 v41, v35, s42, v158
	v_mov_b32_e32 v35, 0
	v_cvt_pk_fp8_f32 v34, v39, v40
	v_cvt_pk_fp8_f32 v35, v38, v41
	v_med3_f32 v39, v44, s42, v158
	v_med3_f32 v40, v45, s42, v158
	v_med3_f32 v36, v36, s42, v158
	v_med3_f32 v37, v37, s42, v158
	v_cvt_pk_fp8_f32 v34, v39, v40 op_sel:[0,0,1]
	v_cvt_pk_fp8_f32 v35, v36, v37 op_sel:[0,0,1]
	v_add_u32_e32 v52, 0x90, v159
	v_mad_i64_i32 v[36:37], s[20:21], v52, s41, v[150:151]
	v_lshl_add_u64 v[36:37], v[36:37], 0, v[148:149]
	global_store_dwordx2 v[36:37], v[34:35], off nt
	v_mul_f32_e32 v34, 0xbfb8aa3b, v30
	v_mul_f32_e32 v35, 0xbfb8aa3b, v31
	v_mul_f32_e32 v26, v30, v26
	v_mul_f32_e32 v27, v31, v27
	v_mul_f32_e32 v30, 0xbfb8aa3b, v32
	v_mul_f32_e32 v31, 0xbfb8aa3b, v33
	v_exp_f32_e32 v30, v30
	v_exp_f32_e32 v31, v31
	v_mul_f32_e32 v28, v32, v28
	v_mul_f32_e32 v32, 0xbfb8aa3b, v22
	v_fmamk_f32 v30, v30, 0x3e000000, v157
	v_fmamk_f32 v31, v31, 0x3e000000, v157
	v_rcp_f32_e32 v30, v30
	v_rcp_f32_e32 v31, v31
	v_exp_f32_e32 v32, v32
	v_mul_f32_e32 v29, v33, v29
	v_mul_f32_e32 v28, v30, v28
	v_mul_f32_e32 v29, v31, v29
	v_fmamk_f32 v30, v32, 0x3e000000, v157
	v_mul_f32_e32 v31, 0xbfb8aa3b, v23
	v_rcp_f32_e32 v30, v30
	v_exp_f32_e32 v31, v31
	v_mul_f32_e32 v18, v22, v18
	v_exp_f32_e32 v34, v34
	v_mul_f32_e32 v22, v30, v18
	v_mul_f32_e32 v18, v23, v19
	v_fmamk_f32 v19, v31, 0x3e000000, v157
	v_mul_f32_e32 v23, 0xbfb8aa3b, v24
	v_exp_f32_e32 v35, v35
	v_rcp_f32_e32 v19, v19
	v_exp_f32_e32 v23, v23
	v_mul_f32_e32 v30, 0xbfb8aa3b, v25
	v_exp_f32_e32 v30, v30
	v_fmamk_f32 v34, v34, 0x3e000000, v157
	v_fmamk_f32 v35, v35, 0x3e000000, v157
	v_mul_f32_e32 v19, v19, v18
	v_fmamk_f32 v18, v23, 0x3e000000, v157
	v_rcp_f32_e32 v34, v34
	v_rcp_f32_e32 v35, v35
	v_rcp_f32_e32 v18, v18
	v_fmamk_f32 v23, v30, 0x3e000000, v157
	v_rcp_f32_e32 v23, v23
	v_mul_f32_e32 v20, v24, v20
	v_mul_f32_e32 v26, v34, v26
	v_mul_f32_e32 v27, v35, v27
	v_mul_f32_e32 v20, v18, v20
	v_mul_f32_e32 v18, v25, v21
	v_mul_f32_e32 v21, v23, v18
	v_med3_f32 v23, v26, s42, v158
	v_med3_f32 v24, v27, s42, v158
	v_mov_b32_e32 v18, 0
	v_med3_f32 v22, v22, s42, v158
	v_med3_f32 v25, v19, s42, v158
	v_mov_b32_e32 v19, 0
	v_cvt_pk_fp8_f32 v18, v23, v24
	v_cvt_pk_fp8_f32 v19, v22, v25
	v_med3_f32 v23, v28, s42, v158
	v_med3_f32 v24, v29, s42, v158
	v_med3_f32 v20, v20, s42, v158
	v_med3_f32 v21, v21, s42, v158
	v_cvt_pk_fp8_f32 v18, v23, v24 op_sel:[0,0,1]
	v_cvt_pk_fp8_f32 v19, v20, v21 op_sel:[0,0,1]
	v_add_u32_e32 v36, 0xa0, v159
	v_mad_i64_i32 v[20:21], s[20:21], v36, s41, v[150:151]
	v_lshl_add_u64 v[20:21], v[20:21], 0, v[148:149]
	global_store_dwordx2 v[20:21], v[18:19], off nt
	v_mul_f32_e32 v18, 0xbfb8aa3b, v14
	v_mul_f32_e32 v19, 0xbfb8aa3b, v15
	v_mul_f32_e32 v10, v14, v10
	v_mul_f32_e32 v11, v15, v11
	v_mul_f32_e32 v14, 0xbfb8aa3b, v16
	v_mul_f32_e32 v15, 0xbfb8aa3b, v17
	v_exp_f32_e32 v14, v14
	v_exp_f32_e32 v15, v15
	v_mul_f32_e32 v12, v16, v12
	v_mul_f32_e32 v16, 0xbfb8aa3b, v6
	v_fmamk_f32 v14, v14, 0x3e000000, v157
	v_fmamk_f32 v15, v15, 0x3e000000, v157
	v_rcp_f32_e32 v14, v14
	v_rcp_f32_e32 v15, v15
	v_exp_f32_e32 v16, v16
	v_mul_f32_e32 v13, v17, v13
	v_mul_f32_e32 v12, v14, v12
	v_mul_f32_e32 v13, v15, v13
	v_fmamk_f32 v14, v16, 0x3e000000, v157
	v_mul_f32_e32 v15, 0xbfb8aa3b, v7
	v_rcp_f32_e32 v14, v14
	v_exp_f32_e32 v15, v15
	v_mul_f32_e32 v2, v6, v2
	v_exp_f32_e32 v18, v18
	v_mul_f32_e32 v6, v14, v2
	v_mul_f32_e32 v2, v7, v3
	v_fmamk_f32 v3, v15, 0x3e000000, v157
	v_mul_f32_e32 v7, 0xbfb8aa3b, v8
	v_exp_f32_e32 v19, v19
	v_rcp_f32_e32 v3, v3
	v_exp_f32_e32 v7, v7
	v_mul_f32_e32 v14, 0xbfb8aa3b, v9
	v_exp_f32_e32 v14, v14
	v_fmamk_f32 v18, v18, 0x3e000000, v157
	v_fmamk_f32 v19, v19, 0x3e000000, v157
	v_mul_f32_e32 v3, v3, v2
	v_fmamk_f32 v2, v7, 0x3e000000, v157
	v_rcp_f32_e32 v18, v18
	v_rcp_f32_e32 v19, v19
	v_rcp_f32_e32 v2, v2
	v_fmamk_f32 v7, v14, 0x3e000000, v157
	v_rcp_f32_e32 v7, v7
	v_mul_f32_e32 v4, v8, v4
	v_mul_f32_e32 v10, v18, v10
	v_mul_f32_e32 v11, v19, v11
	v_mul_f32_e32 v4, v2, v4
	v_mul_f32_e32 v2, v9, v5
	v_mul_f32_e32 v5, v7, v2
	v_med3_f32 v7, v10, s42, v158
	v_med3_f32 v8, v11, s42, v158
	v_mov_b32_e32 v2, 0
	v_med3_f32 v6, v6, s42, v158
	v_med3_f32 v9, v3, s42, v158
	v_mov_b32_e32 v3, 0
	v_cvt_pk_fp8_f32 v2, v7, v8
	v_cvt_pk_fp8_f32 v3, v6, v9
	v_med3_f32 v7, v12, s42, v158
	v_med3_f32 v8, v13, s42, v158
	v_med3_f32 v4, v4, s42, v158
	v_med3_f32 v5, v5, s42, v158
	v_cvt_pk_fp8_f32 v2, v7, v8 op_sel:[0,0,1]
	v_cvt_pk_fp8_f32 v3, v4, v5 op_sel:[0,0,1]
	v_add_u32_e32 v20, 0xb0, v159
	v_mad_i64_i32 v[4:5], s[20:21], v20, s41, v[150:151]
	v_lshl_add_u64 v[4:5], v[4:5], 0, v[148:149]
	s_andn2_b64 vcc, exec, s[0:1]
	s_mov_b64 s[0:1], -1
	global_store_dwordx2 v[4:5], v[2:3], off nt
	s_cbranch_vccnz .LBB0_215
	s_andn2_b64 vcc, exec, s[2:3]
	s_cbranch_vccnz .LBB0_214
	s_barrier
	s_branch .LBB0_214

;     __device__ __forceinline__ void operator()(const f32x4 (&acc)[2][2][4][2], const pg8::Unit& u, int wr, int wc, int fr, int fq) const {
;         const int row0 = u.pm * 256 + wr * 64 + fr, col0 = u.pn * 128 + wc * 32 + 8 * fq;
; #pragma unroll
;         for (int ai = 0; ai < 2; ++ai)
; #pragma unroll
;             for (int m = 0; m < 4; ++m) {
;                 unsigned char* rowp = O + (size_t)(row0 + ai * 128 + m * 16) * DFF + col0;
;                 float v[8];
; #pragma unroll
;                 for (int n = 0; n < 2; ++n)
; #pragma unroll
;                     for (int j = 0; j < 4; ++j) { const float g = acc[ai][0][m][n][j], up = acc[ai][1][m][n][j]; v[4 * n + j] = g * up * __builtin_amdgcn_rcpf(__builtin_fmaf(__builtin_amdgcn_exp2f(-1.44269504089f * g), 1.0f / ACT8_SCALE, 1.0f / ACT8_SCALE)); }
;                 u32x2 w; w.x = pk4_fp8(v[0], v[1], v[2], v[3]); w.y = pk4_fp8(v[4], v[5], v[6], v[7]);
;                 *(u32x2*)rowp = w;
.LBB0_1102:
	v_mul_f32_e32 v150, 0xbfb8aa3b, v126
	v_exp_f32_e32 v160, v150
	v_mul_f32_e32 v150, 0xbfb8aa3b, v127
	v_mul_f32_e32 v122, v126, v122
	v_mul_f32_e32 v123, v127, v123
	v_mul_f32_e32 v126, 0xbfb8aa3b, v128
	v_mul_f32_e32 v127, 0xbfb8aa3b, v129
	v_exp_f32_e32 v126, v126
	v_exp_f32_e32 v127, v127
	v_mul_f32_e32 v124, v128, v124
	v_mul_f32_e32 v128, 0xbfb8aa3b, v118
	v_fmamk_f32 v126, v126, 0x3e000000, v157
	v_fmamk_f32 v127, v127, 0x3e000000, v157
	v_rcp_f32_e32 v126, v126
	v_rcp_f32_e32 v127, v127
	v_exp_f32_e32 v128, v128
	v_mul_f32_e32 v125, v129, v125
	v_mul_f32_e32 v124, v126, v124
	v_mul_f32_e32 v125, v127, v125
	v_fmamk_f32 v126, v128, 0x3e000000, v157
	v_mul_f32_e32 v127, 0xbfb8aa3b, v119
	v_rcp_f32_e32 v126, v126
	v_exp_f32_e32 v127, v127
	v_mul_f32_e32 v114, v118, v114
	v_exp_f32_e32 v161, v150
	v_mul_f32_e32 v118, v126, v114
	v_mul_f32_e32 v114, v119, v115
	v_fmamk_f32 v115, v127, 0x3e000000, v157
	v_mul_f32_e32 v119, 0xbfb8aa3b, v120
	v_rcp_f32_e32 v115, v115
	v_exp_f32_e32 v119, v119
	v_mul_f32_e32 v126, 0xbfb8aa3b, v121
	v_exp_f32_e32 v126, v126
	v_fmamk_f32 v160, v160, 0x3e000000, v157
	v_fmamk_f32 v161, v161, 0x3e000000, v157
	v_mul_f32_e32 v115, v115, v114
	v_fmamk_f32 v114, v119, 0x3e000000, v157
	v_rcp_f32_e32 v160, v160
	v_rcp_f32_e32 v161, v161
	v_rcp_f32_e32 v114, v114
	v_fmamk_f32 v119, v126, 0x3e000000, v157
	v_rcp_f32_e32 v119, v119
	v_mul_f32_e32 v116, v120, v116
	v_mul_f32_e32 v122, v160, v122
	v_mul_f32_e32 v123, v161, v123
	v_mul_f32_e32 v116, v114, v116
	v_mul_f32_e32 v114, v121, v117
	v_mul_f32_e32 v117, v119, v114
	v_med3_f32 v119, v122, s42, v158
	v_med3_f32 v120, v123, s42, v158
	v_mov_b32_e32 v114, 0
	v_med3_f32 v118, v118, s42, v158
	v_med3_f32 v121, v115, s42, v158
	v_mov_b32_e32 v115, 0
	v_cvt_pk_fp8_f32 v114, v119, v120
	v_cvt_pk_fp8_f32 v115, v118, v121
	v_readlane_b32 s6, v253, 50
	v_med3_f32 v119, v124, s42, v158
	v_med3_f32 v120, v125, s42, v158
	v_med3_f32 v116, v116, s42, v158
	v_med3_f32 v117, v117, s42, v158
	v_readlane_b32 s7, v253, 51
	v_cvt_pk_fp8_f32 v114, v119, v120 op_sel:[0,0,1]
	v_cvt_pk_fp8_f32 v115, v116, v117 op_sel:[0,0,1]
	v_lshl_add_u32 v159, s20, 8, v131
	v_lshl_or_b32 v148, s43, 7, v153
	v_mov_b64_e32 v[150:151], s[6:7]
	v_ashrrev_i32_e32 v149, 31, v148
	v_mad_i64_i32 v[116:117], s[22:23], v159, s41, v[150:151]
	v_lshl_add_u64 v[116:117], v[116:117], 0, v[148:149]
	global_store_dwordx2 v[116:117], v[114:115], off nt
	v_mul_f32_e32 v114, 0xbfb8aa3b, v110
	v_mul_f32_e32 v115, 0xbfb8aa3b, v111
	v_mul_f32_e32 v106, v110, v106
	v_mul_f32_e32 v107, v111, v107
	v_mul_f32_e32 v110, 0xbfb8aa3b, v112
	v_mul_f32_e32 v111, 0xbfb8aa3b, v113
	v_exp_f32_e32 v110, v110
	v_exp_f32_e32 v111, v111
	v_mul_f32_e32 v108, v112, v108
	v_mul_f32_e32 v112, 0xbfb8aa3b, v102
	v_fmamk_f32 v110, v110, 0x3e000000, v157
	v_fmamk_f32 v111, v111, 0x3e000000, v157
	v_rcp_f32_e32 v110, v110
	v_rcp_f32_e32 v111, v111
	v_exp_f32_e32 v112, v112
	v_mul_f32_e32 v109, v113, v109
	v_mul_f32_e32 v108, v110, v108
	v_mul_f32_e32 v109, v111, v109
	v_fmamk_f32 v110, v112, 0x3e000000, v157
	v_mul_f32_e32 v111, 0xbfb8aa3b, v103
	v_rcp_f32_e32 v110, v110
	v_exp_f32_e32 v111, v111
	v_mul_f32_e32 v98, v102, v98
	v_exp_f32_e32 v114, v114
	v_mul_f32_e32 v102, v110, v98
	v_mul_f32_e32 v98, v103, v99
	v_fmamk_f32 v99, v111, 0x3e000000, v157
	v_mul_f32_e32 v103, 0xbfb8aa3b, v104
	v_exp_f32_e32 v115, v115
	v_rcp_f32_e32 v99, v99
	v_exp_f32_e32 v103, v103
	v_mul_f32_e32 v110, 0xbfb8aa3b, v105
	v_exp_f32_e32 v110, v110
	v_fmamk_f32 v114, v114, 0x3e000000, v157
	v_fmamk_f32 v115, v115, 0x3e000000, v157
	v_mul_f32_e32 v99, v99, v98
	v_fmamk_f32 v98, v103, 0x3e000000, v157
	v_rcp_f32_e32 v114, v114
	v_rcp_f32_e32 v115, v115
	v_rcp_f32_e32 v98, v98
	v_fmamk_f32 v103, v110, 0x3e000000, v157
	v_rcp_f32_e32 v103, v103
	v_mul_f32_e32 v100, v104, v100
	v_mul_f32_e32 v106, v114, v106
	v_mul_f32_e32 v107, v115, v107
	v_mul_f32_e32 v100, v98, v100
	v_mul_f32_e32 v98, v105, v101
	v_mul_f32_e32 v101, v103, v98
	v_med3_f32 v103, v106, s42, v158
	v_med3_f32 v104, v107, s42, v158
	v_mov_b32_e32 v98, 0
	v_med3_f32 v102, v102, s42, v158
	v_med3_f32 v105, v99, s42, v158
	v_mov_b32_e32 v99, 0
	v_cvt_pk_fp8_f32 v98, v103, v104
	v_cvt_pk_fp8_f32 v99, v102, v105
	v_med3_f32 v103, v108, s42, v158
	v_med3_f32 v104, v109, s42, v158
	v_med3_f32 v100, v100, s42, v158
	v_med3_f32 v101, v101, s42, v158
	v_cvt_pk_fp8_f32 v98, v103, v104 op_sel:[0,0,1]
	v_cvt_pk_fp8_f32 v99, v100, v101 op_sel:[0,0,1]
	v_or_b32_e32 v116, 16, v159
	v_mad_i64_i32 v[100:101], s[22:23], v116, s41, v[150:151]
	v_lshl_add_u64 v[100:101], v[100:101], 0, v[148:149]
	global_store_dwordx2 v[100:101], v[98:99], off nt
	v_mul_f32_e32 v98, 0xbfb8aa3b, v94
	v_mul_f32_e32 v99, 0xbfb8aa3b, v95
	v_mul_f32_e32 v90, v94, v90
	v_mul_f32_e32 v91, v95, v91
	v_mul_f32_e32 v94, 0xbfb8aa3b, v96
	v_mul_f32_e32 v95, 0xbfb8aa3b, v97
	v_exp_f32_e32 v94, v94
	v_exp_f32_e32 v95, v95
	v_mul_f32_e32 v92, v96, v92
	v_mul_f32_e32 v96, 0xbfb8aa3b, v86
	v_fmamk_f32 v94, v94, 0x3e000000, v157
	v_fmamk_f32 v95, v95, 0x3e000000, v157
	v_rcp_f32_e32 v94, v94
	v_rcp_f32_e32 v95, v95
	v_exp_f32_e32 v96, v96
	v_mul_f32_e32 v93, v97, v93
	v_mul_f32_e32 v92, v94, v92
	v_mul_f32_e32 v93, v95, v93
	v_fmamk_f32 v94, v96, 0x3e000000, v157
	v_mul_f32_e32 v95, 0xbfb8aa3b, v87
	v_rcp_f32_e32 v94, v94
	v_exp_f32_e32 v95, v95
	v_mul_f32_e32 v82, v86, v82
	v_exp_f32_e32 v98, v98
	v_mul_f32_e32 v86, v94, v82
	v_mul_f32_e32 v82, v87, v83
	v_fmamk_f32 v83, v95, 0x3e000000, v157
	v_mul_f32_e32 v87, 0xbfb8aa3b, v88
	v_exp_f32_e32 v99, v99
	v_rcp_f32_e32 v83, v83
	v_exp_f32_e32 v87, v87
	v_mul_f32_e32 v94, 0xbfb8aa3b, v89
	v_exp_f32_e32 v94, v94
;     __device__ __forceinline__ void operator()(const f32x4 (&acc)[2][2][4][2], const pg8::Unit& u, int wr, int wc, int fr, int fq) const {
;     ...
;             for (int m = 0; m < 4; ++m) {
;                 unsigned char* rowp = O + (size_t)(row0 + ai * 128 + m * 16) * DFF + col0;
;                 float v[8];
; #pragma unroll
;                 for (int n = 0; n < 2; ++n)
; #pragma unroll
;                     for (int j = 0; j < 4; ++j) { const float g = acc[ai][0][m][n][j], up = acc[ai][1][m][n][j]; v[4 * n + j] = g * up * __builtin_amdgcn_rcpf(__builtin_fmaf(__builtin_amdgcn_exp2f(-1.44269504089f * g), 1.0f / ACT8_SCALE, 1.0f / ACT8_SCALE)); }
;                 u32x2 w; w.x = pk4_fp8(v[0], v[1], v[2], v[3]); w.y = pk4_fp8(v[4], v[5], v[6], v[7]);
;                 *(u32x2*)rowp = w;
	v_fmamk_f32 v98, v98, 0x3e000000, v157
	v_fmamk_f32 v99, v99, 0x3e000000, v157
	v_mul_f32_e32 v83, v83, v82
	v_fmamk_f32 v82, v87, 0x3e000000, v157
	v_rcp_f32_e32 v98, v98
	v_rcp_f32_e32 v99, v99
	v_rcp_f32_e32 v82, v82
	v_fmamk_f32 v87, v94, 0x3e000000, v157
	v_rcp_f32_e32 v87, v87
	v_mul_f32_e32 v84, v88, v84
	v_mul_f32_e32 v90, v98, v90
	v_mul_f32_e32 v91, v99, v91
	v_mul_f32_e32 v84, v82, v84
	v_mul_f32_e32 v82, v89, v85
	v_mul_f32_e32 v85, v87, v82
	v_med3_f32 v87, v90, s42, v158
	v_med3_f32 v88, v91, s42, v158
	v_mov_b32_e32 v82, 0
	v_med3_f32 v86, v86, s42, v158
	v_med3_f32 v89, v83, s42, v158
	v_mov_b32_e32 v83, 0
	v_cvt_pk_fp8_f32 v82, v87, v88
	v_cvt_pk_fp8_f32 v83, v86, v89
	v_med3_f32 v87, v92, s42, v158
	v_med3_f32 v88, v93, s42, v158
	v_med3_f32 v84, v84, s42, v158
	v_med3_f32 v85, v85, s42, v158
	v_cvt_pk_fp8_f32 v82, v87, v88 op_sel:[0,0,1]
	v_cvt_pk_fp8_f32 v83, v84, v85 op_sel:[0,0,1]
	v_or_b32_e32 v100, 32, v159
	v_mad_i64_i32 v[84:85], s[22:23], v100, s41, v[150:151]
	v_lshl_add_u64 v[84:85], v[84:85], 0, v[148:149]
	global_store_dwordx2 v[84:85], v[82:83], off nt
	v_mul_f32_e32 v82, 0xbfb8aa3b, v78
	v_mul_f32_e32 v83, 0xbfb8aa3b, v79
	v_mul_f32_e32 v74, v78, v74
	v_mul_f32_e32 v75, v79, v75
	v_mul_f32_e32 v78, 0xbfb8aa3b, v80
	v_mul_f32_e32 v79, 0xbfb8aa3b, v81
	v_exp_f32_e32 v78, v78
	v_exp_f32_e32 v79, v79
	v_mul_f32_e32 v76, v80, v76
	v_mul_f32_e32 v80, 0xbfb8aa3b, v70
	v_fmamk_f32 v78, v78, 0x3e000000, v157
	v_fmamk_f32 v79, v79, 0x3e000000, v157
	v_rcp_f32_e32 v78, v78
	v_rcp_f32_e32 v79, v79
	v_exp_f32_e32 v80, v80
	v_mul_f32_e32 v77, v81, v77
	v_mul_f32_e32 v76, v78, v76
	v_mul_f32_e32 v77, v79, v77
	v_fmamk_f32 v78, v80, 0x3e000000, v157
	v_mul_f32_e32 v79, 0xbfb8aa3b, v71
	v_rcp_f32_e32 v78, v78
	v_exp_f32_e32 v79, v79
	v_mul_f32_e32 v66, v70, v66
	v_exp_f32_e32 v82, v82
	v_mul_f32_e32 v70, v78, v66
	v_mul_f32_e32 v66, v71, v67
	v_fmamk_f32 v67, v79, 0x3e000000, v157
	v_mul_f32_e32 v71, 0xbfb8aa3b, v72
	v_exp_f32_e32 v83, v83
	v_rcp_f32_e32 v67, v67
	v_exp_f32_e32 v71, v71
	v_mul_f32_e32 v78, 0xbfb8aa3b, v73
	v_exp_f32_e32 v78, v78
	v_fmamk_f32 v82, v82, 0x3e000000, v157
	v_fmamk_f32 v83, v83, 0x3e000000, v157
	v_mul_f32_e32 v67, v67, v66
	v_fmamk_f32 v66, v71, 0x3e000000, v157
	v_rcp_f32_e32 v82, v82
	v_rcp_f32_e32 v83, v83
	v_rcp_f32_e32 v66, v66
	v_fmamk_f32 v71, v78, 0x3e000000, v157
	v_rcp_f32_e32 v71, v71
	v_mul_f32_e32 v68, v72, v68
	v_mul_f32_e32 v74, v82, v74
	v_mul_f32_e32 v75, v83, v75
	v_mul_f32_e32 v68, v66, v68
	v_mul_f32_e32 v66, v73, v69
	v_mul_f32_e32 v69, v71, v66
	v_med3_f32 v71, v74, s42, v158
	v_med3_f32 v72, v75, s42, v158
	v_mov_b32_e32 v66, 0
	v_med3_f32 v70, v70, s42, v158
	v_med3_f32 v73, v67, s42, v158
	v_mov_b32_e32 v67, 0
	v_cvt_pk_fp8_f32 v66, v71, v72
	v_cvt_pk_fp8_f32 v67, v70, v73
	v_med3_f32 v71, v76, s42, v158
	v_med3_f32 v72, v77, s42, v158
	v_med3_f32 v68, v68, s42, v158
	v_med3_f32 v69, v69, s42, v158
	v_cvt_pk_fp8_f32 v66, v71, v72 op_sel:[0,0,1]
	v_cvt_pk_fp8_f32 v67, v68, v69 op_sel:[0,0,1]
	v_or_b32_e32 v84, 48, v159
	v_mad_i64_i32 v[68:69], s[22:23], v84, s41, v[150:151]
	v_lshl_add_u64 v[68:69], v[68:69], 0, v[148:149]
	global_store_dwordx2 v[68:69], v[66:67], off nt
	v_mul_f32_e32 v66, 0xbfb8aa3b, v62
	v_mul_f32_e32 v67, 0xbfb8aa3b, v63
	v_mul_f32_e32 v58, v62, v58
	v_mul_f32_e32 v59, v63, v59
	v_mul_f32_e32 v62, 0xbfb8aa3b, v64
	v_mul_f32_e32 v63, 0xbfb8aa3b, v65
	v_exp_f32_e32 v62, v62
	v_exp_f32_e32 v63, v63
	v_mul_f32_e32 v60, v64, v60
	v_mul_f32_e32 v64, 0xbfb8aa3b, v54
	v_fmamk_f32 v62, v62, 0x3e000000, v157
	v_fmamk_f32 v63, v63, 0x3e000000, v157
	v_rcp_f32_e32 v62, v62
	v_rcp_f32_e32 v63, v63
	v_exp_f32_e32 v64, v64
	v_mul_f32_e32 v61, v65, v61
	v_mul_f32_e32 v60, v62, v60
	v_mul_f32_e32 v61, v63, v61
	v_fmamk_f32 v62, v64, 0x3e000000, v157
	v_mul_f32_e32 v63, 0xbfb8aa3b, v55
	v_rcp_f32_e32 v62, v62
	v_exp_f32_e32 v63, v63
	v_mul_f32_e32 v50, v54, v50
	v_exp_f32_e32 v66, v66
	v_mul_f32_e32 v54, v62, v50
	v_mul_f32_e32 v50, v55, v51
	v_fmamk_f32 v51, v63, 0x3e000000, v157
	v_mul_f32_e32 v55, 0xbfb8aa3b, v56
	v_exp_f32_e32 v67, v67
	v_rcp_f32_e32 v51, v51
	v_exp_f32_e32 v55, v55
	v_mul_f32_e32 v62, 0xbfb8aa3b, v57
	v_exp_f32_e32 v62, v62
	v_fmamk_f32 v66, v66, 0x3e000000, v157
	v_fmamk_f32 v67, v67, 0x3e000000, v157
	v_mul_f32_e32 v51, v51, v50
	v_fmamk_f32 v50, v55, 0x3e000000, v157
	v_rcp_f32_e32 v66, v66
	v_rcp_f32_e32 v67, v67
	v_rcp_f32_e32 v50, v50
	v_fmamk_f32 v55, v62, 0x3e000000, v157
	v_rcp_f32_e32 v55, v55
	v_mul_f32_e32 v52, v56, v52
	v_mul_f32_e32 v58, v66, v58
	v_mul_f32_e32 v59, v67, v59
	v_mul_f32_e32 v52, v50, v52
	v_mul_f32_e32 v50, v57, v53
	v_mul_f32_e32 v53, v55, v50
	v_med3_f32 v55, v58, s42, v158
	v_med3_f32 v56, v59, s42, v158
	v_mov_b32_e32 v50, 0
	v_med3_f32 v54, v54, s42, v158
	v_med3_f32 v57, v51, s42, v158
	v_mov_b32_e32 v51, 0
	v_cvt_pk_fp8_f32 v50, v55, v56
	v_cvt_pk_fp8_f32 v51, v54, v57
	v_med3_f32 v55, v60, s42, v158
	v_med3_f32 v56, v61, s42, v158
	v_med3_f32 v52, v52, s42, v158
	v_med3_f32 v53, v53, s42, v158
	v_cvt_pk_fp8_f32 v50, v55, v56 op_sel:[0,0,1]
	v_cvt_pk_fp8_f32 v51, v52, v53 op_sel:[0,0,1]
	v_add_u32_e32 v68, 0x80, v159
	v_mad_i64_i32 v[52:53], s[22:23], v68, s41, v[150:151]
	v_lshl_add_u64 v[52:53], v[52:53], 0, v[148:149]
	global_store_dwordx2 v[52:53], v[50:51], off nt
	v_mul_f32_e32 v50, 0xbfb8aa3b, v46
	v_mul_f32_e32 v51, 0xbfb8aa3b, v47
	v_mul_f32_e32 v42, v46, v42
	v_mul_f32_e32 v43, v47, v43
	v_mul_f32_e32 v46, 0xbfb8aa3b, v48
	v_mul_f32_e32 v47, 0xbfb8aa3b, v49
	v_exp_f32_e32 v46, v46
	v_exp_f32_e32 v47, v47
	v_mul_f32_e32 v44, v48, v44
	v_mul_f32_e32 v48, 0xbfb8aa3b, v38
	v_fmamk_f32 v46, v46, 0x3e000000, v157
;     __device__ __forceinline__ void operator()(const f32x4 (&acc)[2][2][4][2], const pg8::Unit& u, int wr, int wc, int fr, int fq) const {
;     ...
;             for (int m = 0; m < 4; ++m) {
;                 unsigned char* rowp = O + (size_t)(row0 + ai * 128 + m * 16) * DFF + col0;
;                 float v[8];
; #pragma unroll
;                 for (int n = 0; n < 2; ++n)
; #pragma unroll
;                     for (int j = 0; j < 4; ++j) { const float g = acc[ai][0][m][n][j], up = acc[ai][1][m][n][j]; v[4 * n + j] = g * up * __builtin_amdgcn_rcpf(__builtin_fmaf(__builtin_amdgcn_exp2f(-1.44269504089f * g), 1.0f / ACT8_SCALE, 1.0f / ACT8_SCALE)); }
;                 u32x2 w; w.x = pk4_fp8(v[0], v[1], v[2], v[3]); w.y = pk4_fp8(v[4], v[5], v[6], v[7]);
;                 *(u32x2*)rowp = w;
	v_fmamk_f32 v47, v47, 0x3e000000, v157
	v_rcp_f32_e32 v46, v46
	v_rcp_f32_e32 v47, v47
	v_exp_f32_e32 v48, v48
	v_mul_f32_e32 v45, v49, v45
	v_mul_f32_e32 v44, v46, v44
	v_mul_f32_e32 v45, v47, v45
	v_fmamk_f32 v46, v48, 0x3e000000, v157
	v_mul_f32_e32 v47, 0xbfb8aa3b, v39
	v_rcp_f32_e32 v46, v46
	v_exp_f32_e32 v47, v47
	v_mul_f32_e32 v34, v38, v34
	v_exp_f32_e32 v50, v50
	v_mul_f32_e32 v38, v46, v34
	v_mul_f32_e32 v34, v39, v35
	v_fmamk_f32 v35, v47, 0x3e000000, v157
	v_mul_f32_e32 v39, 0xbfb8aa3b, v40
	v_exp_f32_e32 v51, v51
	v_rcp_f32_e32 v35, v35
	v_exp_f32_e32 v39, v39
	v_mul_f32_e32 v46, 0xbfb8aa3b, v41
	v_exp_f32_e32 v46, v46
	v_fmamk_f32 v50, v50, 0x3e000000, v157
	v_fmamk_f32 v51, v51, 0x3e000000, v157
	v_mul_f32_e32 v35, v35, v34
	v_fmamk_f32 v34, v39, 0x3e000000, v157
	v_rcp_f32_e32 v50, v50
	v_rcp_f32_e32 v51, v51
	v_rcp_f32_e32 v34, v34
	v_fmamk_f32 v39, v46, 0x3e000000, v157
	v_rcp_f32_e32 v39, v39
	v_mul_f32_e32 v36, v40, v36
	v_mul_f32_e32 v42, v50, v42
	v_mul_f32_e32 v43, v51, v43
	v_mul_f32_e32 v36, v34, v36
	v_mul_f32_e32 v34, v41, v37
	v_mul_f32_e32 v37, v39, v34
	v_med3_f32 v39, v42, s42, v158
	v_med3_f32 v40, v43, s42, v158
	v_mov_b32_e32 v34, 0
	v_med3_f32 v38, v38, s42, v158
	v_med3_f32 v41, v35, s42, v158
	v_mov_b32_e32 v35, 0
	v_cvt_pk_fp8_f32 v34, v39, v40
	v_cvt_pk_fp8_f32 v35, v38, v41
	v_med3_f32 v39, v44, s42, v158
	v_med3_f32 v40, v45, s42, v158
	v_med3_f32 v36, v36, s42, v158
	v_med3_f32 v37, v37, s42, v158
	v_cvt_pk_fp8_f32 v34, v39, v40 op_sel:[0,0,1]
	v_cvt_pk_fp8_f32 v35, v36, v37 op_sel:[0,0,1]
	v_add_u32_e32 v52, 0x90, v159
	v_mad_i64_i32 v[36:37], s[22:23], v52, s41, v[150:151]
	v_lshl_add_u64 v[36:37], v[36:37], 0, v[148:149]
	global_store_dwordx2 v[36:37], v[34:35], off nt
	v_mul_f32_e32 v34, 0xbfb8aa3b, v30
	v_mul_f32_e32 v35, 0xbfb8aa3b, v31
	v_mul_f32_e32 v26, v30, v26
	v_mul_f32_e32 v27, v31, v27
	v_mul_f32_e32 v30, 0xbfb8aa3b, v32
	v_mul_f32_e32 v31, 0xbfb8aa3b, v33
	v_exp_f32_e32 v30, v30
	v_exp_f32_e32 v31, v31
	v_mul_f32_e32 v28, v32, v28
	v_mul_f32_e32 v32, 0xbfb8aa3b, v22
	v_fmamk_f32 v30, v30, 0x3e000000, v157
	v_fmamk_f32 v31, v31, 0x3e000000, v157
	v_rcp_f32_e32 v30, v30
	v_rcp_f32_e32 v31, v31
	v_exp_f32_e32 v32, v32
	v_mul_f32_e32 v29, v33, v29
	v_mul_f32_e32 v28, v30, v28
	v_mul_f32_e32 v29, v31, v29
	v_fmamk_f32 v30, v32, 0x3e000000, v157
	v_mul_f32_e32 v31, 0xbfb8aa3b, v23
	v_rcp_f32_e32 v30, v30
	v_exp_f32_e32 v31, v31
	v_mul_f32_e32 v18, v22, v18
	v_exp_f32_e32 v34, v34
	v_mul_f32_e32 v22, v30, v18
	v_mul_f32_e32 v18, v23, v19
	v_fmamk_f32 v19, v31, 0x3e000000, v157
	v_mul_f32_e32 v23, 0xbfb8aa3b, v24
	v_exp_f32_e32 v35, v35
	v_rcp_f32_e32 v19, v19
	v_exp_f32_e32 v23, v23
	v_mul_f32_e32 v30, 0xbfb8aa3b, v25
	v_exp_f32_e32 v30, v30
	v_fmamk_f32 v34, v34, 0x3e000000, v157
	v_fmamk_f32 v35, v35, 0x3e000000, v157
	v_mul_f32_e32 v19, v19, v18
	v_fmamk_f32 v18, v23, 0x3e000000, v157
	v_rcp_f32_e32 v34, v34
	v_rcp_f32_e32 v35, v35
	v_rcp_f32_e32 v18, v18
	v_fmamk_f32 v23, v30, 0x3e000000, v157
	v_rcp_f32_e32 v23, v23
	v_mul_f32_e32 v20, v24, v20
	v_mul_f32_e32 v26, v34, v26
	v_mul_f32_e32 v27, v35, v27
	v_mul_f32_e32 v20, v18, v20
	v_mul_f32_e32 v18, v25, v21
	v_mul_f32_e32 v21, v23, v18
	v_med3_f32 v23, v26, s42, v158
	v_med3_f32 v24, v27, s42, v158
	v_mov_b32_e32 v18, 0
	v_med3_f32 v22, v22, s42, v158
	v_med3_f32 v25, v19, s42, v158
	v_mov_b32_e32 v19, 0
	v_cvt_pk_fp8_f32 v18, v23, v24
	v_cvt_pk_fp8_f32 v19, v22, v25
	v_med3_f32 v23, v28, s42, v158
	v_med3_f32 v24, v29, s42, v158
	v_med3_f32 v20, v20, s42, v158
	v_med3_f32 v21, v21, s42, v158
	v_cvt_pk_fp8_f32 v18, v23, v24 op_sel:[0,0,1]
	v_cvt_pk_fp8_f32 v19, v20, v21 op_sel:[0,0,1]
	v_add_u32_e32 v36, 0xa0, v159
	v_mad_i64_i32 v[20:21], s[22:23], v36, s41, v[150:151]
	v_lshl_add_u64 v[20:21], v[20:21], 0, v[148:149]
	global_store_dwordx2 v[20:21], v[18:19], off nt
	v_mul_f32_e32 v18, 0xbfb8aa3b, v14
	v_mul_f32_e32 v19, 0xbfb8aa3b, v15
	v_mul_f32_e32 v10, v14, v10
	v_mul_f32_e32 v11, v15, v11
	v_mul_f32_e32 v14, 0xbfb8aa3b, v16
	v_mul_f32_e32 v15, 0xbfb8aa3b, v17
	v_exp_f32_e32 v14, v14
	v_exp_f32_e32 v15, v15
	v_mul_f32_e32 v12, v16, v12
	v_mul_f32_e32 v16, 0xbfb8aa3b, v6
	v_fmamk_f32 v14, v14, 0x3e000000, v157
	v_fmamk_f32 v15, v15, 0x3e000000, v157
	v_rcp_f32_e32 v14, v14
	v_rcp_f32_e32 v15, v15
	v_exp_f32_e32 v16, v16
	v_mul_f32_e32 v13, v17, v13
	v_mul_f32_e32 v12, v14, v12
	v_mul_f32_e32 v13, v15, v13
	v_fmamk_f32 v14, v16, 0x3e000000, v157
	v_mul_f32_e32 v15, 0xbfb8aa3b, v7
	v_rcp_f32_e32 v14, v14
	v_exp_f32_e32 v15, v15
	v_mul_f32_e32 v2, v6, v2
	v_exp_f32_e32 v18, v18
	v_mul_f32_e32 v6, v14, v2
	v_mul_f32_e32 v2, v7, v3
	v_fmamk_f32 v3, v15, 0x3e000000, v157
	v_mul_f32_e32 v7, 0xbfb8aa3b, v8
	v_exp_f32_e32 v19, v19
	v_rcp_f32_e32 v3, v3
	v_exp_f32_e32 v7, v7
	v_mul_f32_e32 v14, 0xbfb8aa3b, v9
	v_exp_f32_e32 v14, v14
	v_fmamk_f32 v18, v18, 0x3e000000, v157
	v_fmamk_f32 v19, v19, 0x3e000000, v157
	v_mul_f32_e32 v3, v3, v2
	v_fmamk_f32 v2, v7, 0x3e000000, v157
	v_rcp_f32_e32 v18, v18
	v_rcp_f32_e32 v19, v19
	v_rcp_f32_e32 v2, v2
	v_fmamk_f32 v7, v14, 0x3e000000, v157
	v_rcp_f32_e32 v7, v7
	v_mul_f32_e32 v4, v8, v4
	v_mul_f32_e32 v10, v18, v10
	v_mul_f32_e32 v11, v19, v11
	v_mul_f32_e32 v4, v2, v4
	v_mul_f32_e32 v2, v9, v5
	v_mul_f32_e32 v5, v7, v2
	v_med3_f32 v7, v10, s42, v158
	v_med3_f32 v8, v11, s42, v158
	v_mov_b32_e32 v2, 0
	v_med3_f32 v6, v6, s42, v158
	v_med3_f32 v9, v3, s42, v158
	v_mov_b32_e32 v3, 0
	v_cvt_pk_fp8_f32 v2, v7, v8
	v_cvt_pk_fp8_f32 v3, v6, v9
	v_med3_f32 v7, v12, s42, v158
	v_med3_f32 v8, v13, s42, v158
	v_med3_f32 v4, v4, s42, v158
	v_med3_f32 v5, v5, s42, v158
	v_cvt_pk_fp8_f32 v2, v7, v8 op_sel:[0,0,1]
	v_cvt_pk_fp8_f32 v3, v4, v5 op_sel:[0,0,1]
	v_add_u32_e32 v20, 0xb0, v159
	v_mad_i64_i32 v[4:5], s[22:23], v20, s41, v[150:151]
	v_lshl_add_u64 v[4:5], v[4:5], 0, v[148:149]
	s_andn2_b64 vcc, exec, s[0:1]
	s_mov_b64 s[0:1], -1
	global_store_dwordx2 v[4:5], v[2:3], off nt
	s_cbranch_vccnz .LBB0_1095
	s_andn2_b64 vcc, exec, s[2:3]
	s_cbranch_vccnz .LBB0_1094
	s_barrier
	s_branch .LBB0_1094

;     __device__ __forceinline__ void operator()(const f32x4 (&acc)[2][2][4][2], const pg8::Unit& u, int wr, int wc, int fr, int fq) const {
;         const int row0 = u.pm * 256 + wr * 64 + fr, col0 = u.pn * 128 + wc * 32 + 8 * fq;
; #pragma unroll
;         for (int ai = 0; ai < 2; ++ai)
; #pragma unroll
;             for (int m = 0; m < 4; ++m) {
;                 unsigned char* rowp = O + (size_t)(row0 + ai * 128 + m * 16) * DFF + col0;
;                 float v[8];
; #pragma unroll
;                 for (int n = 0; n < 2; ++n)
; #pragma unroll
;                     for (int j = 0; j < 4; ++j) { const float g = acc[ai][0][m][n][j], up = acc[ai][1][m][n][j]; v[4 * n + j] = g * up * __builtin_amdgcn_rcpf(__builtin_fmaf(__builtin_amdgcn_exp2f(-1.44269504089f * g), 1.0f / ACT8_SCALE, 1.0f / ACT8_SCALE)); }
;                 u32x2 w; w.x = pk4_fp8(v[0], v[1], v[2], v[3]); w.y = pk4_fp8(v[4], v[5], v[6], v[7]);
;                 *(u32x2*)rowp = w;
.LBB0_1451:
	v_mul_f32_e32 v150, 0xbfb8aa3b, v126
	v_exp_f32_e32 v160, v150
	v_mul_f32_e32 v150, 0xbfb8aa3b, v127
	v_mul_f32_e32 v122, v126, v122
	v_mul_f32_e32 v123, v127, v123
	v_mul_f32_e32 v126, 0xbfb8aa3b, v128
	v_mul_f32_e32 v127, 0xbfb8aa3b, v129
	v_exp_f32_e32 v126, v126
	v_exp_f32_e32 v127, v127
	v_mul_f32_e32 v124, v128, v124
	v_mul_f32_e32 v128, 0xbfb8aa3b, v118
	v_fmamk_f32 v126, v126, 0x3e000000, v157
	v_fmamk_f32 v127, v127, 0x3e000000, v157
	v_rcp_f32_e32 v126, v126
	v_rcp_f32_e32 v127, v127
	v_exp_f32_e32 v128, v128
	v_mul_f32_e32 v125, v129, v125
	v_mul_f32_e32 v124, v126, v124
	v_mul_f32_e32 v125, v127, v125
	v_fmamk_f32 v126, v128, 0x3e000000, v157
	v_mul_f32_e32 v127, 0xbfb8aa3b, v119
	v_rcp_f32_e32 v126, v126
	v_exp_f32_e32 v127, v127
	v_mul_f32_e32 v114, v118, v114
	v_exp_f32_e32 v161, v150
	v_mul_f32_e32 v118, v126, v114
	v_mul_f32_e32 v114, v119, v115
	v_fmamk_f32 v115, v127, 0x3e000000, v157
	v_mul_f32_e32 v119, 0xbfb8aa3b, v120
	v_rcp_f32_e32 v115, v115
	v_exp_f32_e32 v119, v119
	v_mul_f32_e32 v126, 0xbfb8aa3b, v121
	v_exp_f32_e32 v126, v126
	v_fmamk_f32 v160, v160, 0x3e000000, v157
	v_fmamk_f32 v161, v161, 0x3e000000, v157
	v_mul_f32_e32 v115, v115, v114
	v_fmamk_f32 v114, v119, 0x3e000000, v157
	v_rcp_f32_e32 v160, v160
	v_rcp_f32_e32 v161, v161
	v_rcp_f32_e32 v114, v114
	v_fmamk_f32 v119, v126, 0x3e000000, v157
	v_rcp_f32_e32 v119, v119
	v_mul_f32_e32 v116, v120, v116
	v_mul_f32_e32 v122, v160, v122
	v_mul_f32_e32 v123, v161, v123
	v_mul_f32_e32 v116, v114, v116
	v_mul_f32_e32 v114, v121, v117
	v_mul_f32_e32 v117, v119, v114
	v_med3_f32 v119, v122, s44, v158
	v_med3_f32 v120, v123, s44, v158
	v_mov_b32_e32 v114, 0
	v_med3_f32 v118, v118, s44, v158
	v_med3_f32 v121, v115, s44, v158
	v_mov_b32_e32 v115, 0
	v_cvt_pk_fp8_f32 v114, v119, v120
	v_cvt_pk_fp8_f32 v115, v118, v121
	v_readlane_b32 s24, v253, 50
	v_med3_f32 v119, v124, s44, v158
	v_med3_f32 v120, v125, s44, v158
	v_med3_f32 v116, v116, s44, v158
	v_med3_f32 v117, v117, s44, v158
	v_readlane_b32 s25, v253, 51
	v_cvt_pk_fp8_f32 v114, v119, v120 op_sel:[0,0,1]
	v_cvt_pk_fp8_f32 v115, v116, v117 op_sel:[0,0,1]
	v_lshl_add_u32 v159, s22, 8, v131
	v_lshl_or_b32 v148, s45, 7, v153
	v_mov_b64_e32 v[150:151], s[24:25]
	v_ashrrev_i32_e32 v149, 31, v148
	v_mad_i64_i32 v[116:117], s[24:25], v159, s43, v[150:151]
	v_lshl_add_u64 v[116:117], v[116:117], 0, v[148:149]
	global_store_dwordx2 v[116:117], v[114:115], off nt
	v_mul_f32_e32 v114, 0xbfb8aa3b, v110
	v_mul_f32_e32 v115, 0xbfb8aa3b, v111
	v_mul_f32_e32 v106, v110, v106
	v_mul_f32_e32 v107, v111, v107
	v_mul_f32_e32 v110, 0xbfb8aa3b, v112
	v_mul_f32_e32 v111, 0xbfb8aa3b, v113
	v_exp_f32_e32 v110, v110
	v_exp_f32_e32 v111, v111
	v_mul_f32_e32 v108, v112, v108
	v_mul_f32_e32 v112, 0xbfb8aa3b, v102
	v_fmamk_f32 v110, v110, 0x3e000000, v157
	v_fmamk_f32 v111, v111, 0x3e000000, v157
	v_rcp_f32_e32 v110, v110
	v_rcp_f32_e32 v111, v111
	v_exp_f32_e32 v112, v112
	v_mul_f32_e32 v109, v113, v109
	v_mul_f32_e32 v108, v110, v108
	v_mul_f32_e32 v109, v111, v109
	v_fmamk_f32 v110, v112, 0x3e000000, v157
	v_mul_f32_e32 v111, 0xbfb8aa3b, v103
	v_rcp_f32_e32 v110, v110
	v_exp_f32_e32 v111, v111
	v_mul_f32_e32 v98, v102, v98
	v_exp_f32_e32 v114, v114
	v_mul_f32_e32 v102, v110, v98
	v_mul_f32_e32 v98, v103, v99
	v_fmamk_f32 v99, v111, 0x3e000000, v157
	v_mul_f32_e32 v103, 0xbfb8aa3b, v104
	v_exp_f32_e32 v115, v115
	v_rcp_f32_e32 v99, v99
	v_exp_f32_e32 v103, v103
	v_mul_f32_e32 v110, 0xbfb8aa3b, v105
	v_exp_f32_e32 v110, v110
	v_fmamk_f32 v114, v114, 0x3e000000, v157
	v_fmamk_f32 v115, v115, 0x3e000000, v157
	v_mul_f32_e32 v99, v99, v98
	v_fmamk_f32 v98, v103, 0x3e000000, v157
	v_rcp_f32_e32 v114, v114
	v_rcp_f32_e32 v115, v115
	v_rcp_f32_e32 v98, v98
	v_fmamk_f32 v103, v110, 0x3e000000, v157
	v_rcp_f32_e32 v103, v103
	v_mul_f32_e32 v100, v104, v100
	v_mul_f32_e32 v106, v114, v106
	v_mul_f32_e32 v107, v115, v107
	v_mul_f32_e32 v100, v98, v100
	v_mul_f32_e32 v98, v105, v101
	v_mul_f32_e32 v101, v103, v98
	v_med3_f32 v103, v106, s44, v158
	v_med3_f32 v104, v107, s44, v158
	v_mov_b32_e32 v98, 0
	v_med3_f32 v102, v102, s44, v158
	v_med3_f32 v105, v99, s44, v158
	v_mov_b32_e32 v99, 0
	v_cvt_pk_fp8_f32 v98, v103, v104
	v_cvt_pk_fp8_f32 v99, v102, v105
	v_med3_f32 v103, v108, s44, v158
	v_med3_f32 v104, v109, s44, v158
	v_med3_f32 v100, v100, s44, v158
	v_med3_f32 v101, v101, s44, v158
	v_cvt_pk_fp8_f32 v98, v103, v104 op_sel:[0,0,1]
	v_cvt_pk_fp8_f32 v99, v100, v101 op_sel:[0,0,1]
	v_or_b32_e32 v116, 16, v159
	v_mad_i64_i32 v[100:101], s[24:25], v116, s43, v[150:151]
	v_lshl_add_u64 v[100:101], v[100:101], 0, v[148:149]
	global_store_dwordx2 v[100:101], v[98:99], off nt
	v_mul_f32_e32 v98, 0xbfb8aa3b, v94
	v_mul_f32_e32 v99, 0xbfb8aa3b, v95
	v_mul_f32_e32 v90, v94, v90
	v_mul_f32_e32 v91, v95, v91
	v_mul_f32_e32 v94, 0xbfb8aa3b, v96
	v_mul_f32_e32 v95, 0xbfb8aa3b, v97
	v_exp_f32_e32 v94, v94
	v_exp_f32_e32 v95, v95
	v_mul_f32_e32 v92, v96, v92
	v_mul_f32_e32 v96, 0xbfb8aa3b, v86
	v_fmamk_f32 v94, v94, 0x3e000000, v157
	v_fmamk_f32 v95, v95, 0x3e000000, v157
	v_rcp_f32_e32 v94, v94
	v_rcp_f32_e32 v95, v95
	v_exp_f32_e32 v96, v96
	v_mul_f32_e32 v93, v97, v93
	v_mul_f32_e32 v92, v94, v92
	v_mul_f32_e32 v93, v95, v93
	v_fmamk_f32 v94, v96, 0x3e000000, v157
	v_mul_f32_e32 v95, 0xbfb8aa3b, v87
	v_rcp_f32_e32 v94, v94
	v_exp_f32_e32 v95, v95
	v_mul_f32_e32 v82, v86, v82
	v_exp_f32_e32 v98, v98
	v_mul_f32_e32 v86, v94, v82
	v_mul_f32_e32 v82, v87, v83
	v_fmamk_f32 v83, v95, 0x3e000000, v157
	v_mul_f32_e32 v87, 0xbfb8aa3b, v88
	v_exp_f32_e32 v99, v99
	v_rcp_f32_e32 v83, v83
	v_exp_f32_e32 v87, v87
	v_mul_f32_e32 v94, 0xbfb8aa3b, v89
;     __device__ __forceinline__ void operator()(const f32x4 (&acc)[2][2][4][2], const pg8::Unit& u, int wr, int wc, int fr, int fq) const {
;     ...
;             for (int m = 0; m < 4; ++m) {
;                 unsigned char* rowp = O + (size_t)(row0 + ai * 128 + m * 16) * DFF + col0;
;                 float v[8];
; #pragma unroll
;                 for (int n = 0; n < 2; ++n)
; #pragma unroll
;                     for (int j = 0; j < 4; ++j) { const float g = acc[ai][0][m][n][j], up = acc[ai][1][m][n][j]; v[4 * n + j] = g * up * __builtin_amdgcn_rcpf(__builtin_fmaf(__builtin_amdgcn_exp2f(-1.44269504089f * g), 1.0f / ACT8_SCALE, 1.0f / ACT8_SCALE)); }
;                 u32x2 w; w.x = pk4_fp8(v[0], v[1], v[2], v[3]); w.y = pk4_fp8(v[4], v[5], v[6], v[7]);
;                 *(u32x2*)rowp = w;
	v_exp_f32_e32 v94, v94
	v_fmamk_f32 v98, v98, 0x3e000000, v157
	v_fmamk_f32 v99, v99, 0x3e000000, v157
	v_mul_f32_e32 v83, v83, v82
	v_fmamk_f32 v82, v87, 0x3e000000, v157
	v_rcp_f32_e32 v98, v98
	v_rcp_f32_e32 v99, v99
	v_rcp_f32_e32 v82, v82
	v_fmamk_f32 v87, v94, 0x3e000000, v157
	v_rcp_f32_e32 v87, v87
	v_mul_f32_e32 v84, v88, v84
	v_mul_f32_e32 v90, v98, v90
	v_mul_f32_e32 v91, v99, v91
	v_mul_f32_e32 v84, v82, v84
	v_mul_f32_e32 v82, v89, v85
	v_mul_f32_e32 v85, v87, v82
	v_med3_f32 v87, v90, s44, v158
	v_med3_f32 v88, v91, s44, v158
	v_mov_b32_e32 v82, 0
	v_med3_f32 v86, v86, s44, v158
	v_med3_f32 v89, v83, s44, v158
	v_mov_b32_e32 v83, 0
	v_cvt_pk_fp8_f32 v82, v87, v88
	v_cvt_pk_fp8_f32 v83, v86, v89
	v_med3_f32 v87, v92, s44, v158
	v_med3_f32 v88, v93, s44, v158
	v_med3_f32 v84, v84, s44, v158
	v_med3_f32 v85, v85, s44, v158
	v_cvt_pk_fp8_f32 v82, v87, v88 op_sel:[0,0,1]
	v_cvt_pk_fp8_f32 v83, v84, v85 op_sel:[0,0,1]
	v_or_b32_e32 v100, 32, v159
	v_mad_i64_i32 v[84:85], s[24:25], v100, s43, v[150:151]
	v_lshl_add_u64 v[84:85], v[84:85], 0, v[148:149]
	global_store_dwordx2 v[84:85], v[82:83], off nt
	v_mul_f32_e32 v82, 0xbfb8aa3b, v78
	v_mul_f32_e32 v83, 0xbfb8aa3b, v79
	v_mul_f32_e32 v74, v78, v74
	v_mul_f32_e32 v75, v79, v75
	v_mul_f32_e32 v78, 0xbfb8aa3b, v80
	v_mul_f32_e32 v79, 0xbfb8aa3b, v81
	v_exp_f32_e32 v78, v78
	v_exp_f32_e32 v79, v79
	v_mul_f32_e32 v76, v80, v76
	v_mul_f32_e32 v80, 0xbfb8aa3b, v70
	v_fmamk_f32 v78, v78, 0x3e000000, v157
	v_fmamk_f32 v79, v79, 0x3e000000, v157
	v_rcp_f32_e32 v78, v78
	v_rcp_f32_e32 v79, v79
	v_exp_f32_e32 v80, v80
	v_mul_f32_e32 v77, v81, v77
	v_mul_f32_e32 v76, v78, v76
	v_mul_f32_e32 v77, v79, v77
	v_fmamk_f32 v78, v80, 0x3e000000, v157
	v_mul_f32_e32 v79, 0xbfb8aa3b, v71
	v_rcp_f32_e32 v78, v78
	v_exp_f32_e32 v79, v79
	v_mul_f32_e32 v66, v70, v66
	v_exp_f32_e32 v82, v82
	v_mul_f32_e32 v70, v78, v66
	v_mul_f32_e32 v66, v71, v67
	v_fmamk_f32 v67, v79, 0x3e000000, v157
	v_mul_f32_e32 v71, 0xbfb8aa3b, v72
	v_exp_f32_e32 v83, v83
	v_rcp_f32_e32 v67, v67
	v_exp_f32_e32 v71, v71
	v_mul_f32_e32 v78, 0xbfb8aa3b, v73
	v_exp_f32_e32 v78, v78
	v_fmamk_f32 v82, v82, 0x3e000000, v157
	v_fmamk_f32 v83, v83, 0x3e000000, v157
	v_mul_f32_e32 v67, v67, v66
	v_fmamk_f32 v66, v71, 0x3e000000, v157
	v_rcp_f32_e32 v82, v82
	v_rcp_f32_e32 v83, v83
	v_rcp_f32_e32 v66, v66
	v_fmamk_f32 v71, v78, 0x3e000000, v157
	v_rcp_f32_e32 v71, v71
	v_mul_f32_e32 v68, v72, v68
	v_mul_f32_e32 v74, v82, v74
	v_mul_f32_e32 v75, v83, v75
	v_mul_f32_e32 v68, v66, v68
	v_mul_f32_e32 v66, v73, v69
	v_mul_f32_e32 v69, v71, v66
	v_med3_f32 v71, v74, s44, v158
	v_med3_f32 v72, v75, s44, v158
	v_mov_b32_e32 v66, 0
	v_med3_f32 v70, v70, s44, v158
	v_med3_f32 v73, v67, s44, v158
	v_mov_b32_e32 v67, 0
	v_cvt_pk_fp8_f32 v66, v71, v72
	v_cvt_pk_fp8_f32 v67, v70, v73
	v_med3_f32 v71, v76, s44, v158
	v_med3_f32 v72, v77, s44, v158
	v_med3_f32 v68, v68, s44, v158
	v_med3_f32 v69, v69, s44, v158
	v_cvt_pk_fp8_f32 v66, v71, v72 op_sel:[0,0,1]
	v_cvt_pk_fp8_f32 v67, v68, v69 op_sel:[0,0,1]
	v_or_b32_e32 v84, 48, v159
	v_mad_i64_i32 v[68:69], s[24:25], v84, s43, v[150:151]
	v_lshl_add_u64 v[68:69], v[68:69], 0, v[148:149]
	global_store_dwordx2 v[68:69], v[66:67], off nt
	v_mul_f32_e32 v66, 0xbfb8aa3b, v62
	v_mul_f32_e32 v67, 0xbfb8aa3b, v63
	v_mul_f32_e32 v58, v62, v58
	v_mul_f32_e32 v59, v63, v59
	v_mul_f32_e32 v62, 0xbfb8aa3b, v64
	v_mul_f32_e32 v63, 0xbfb8aa3b, v65
	v_exp_f32_e32 v62, v62
	v_exp_f32_e32 v63, v63
	v_mul_f32_e32 v60, v64, v60
	v_mul_f32_e32 v64, 0xbfb8aa3b, v54
	v_fmamk_f32 v62, v62, 0x3e000000, v157
	v_fmamk_f32 v63, v63, 0x3e000000, v157
	v_rcp_f32_e32 v62, v62
	v_rcp_f32_e32 v63, v63
	v_exp_f32_e32 v64, v64
	v_mul_f32_e32 v61, v65, v61
	v_mul_f32_e32 v60, v62, v60
	v_mul_f32_e32 v61, v63, v61
	v_fmamk_f32 v62, v64, 0x3e000000, v157
	v_mul_f32_e32 v63, 0xbfb8aa3b, v55
	v_rcp_f32_e32 v62, v62
	v_exp_f32_e32 v63, v63
	v_mul_f32_e32 v50, v54, v50
	v_exp_f32_e32 v66, v66
	v_mul_f32_e32 v54, v62, v50
	v_mul_f32_e32 v50, v55, v51
	v_fmamk_f32 v51, v63, 0x3e000000, v157
	v_mul_f32_e32 v55, 0xbfb8aa3b, v56
	v_exp_f32_e32 v67, v67
	v_rcp_f32_e32 v51, v51
	v_exp_f32_e32 v55, v55
	v_mul_f32_e32 v62, 0xbfb8aa3b, v57
	v_exp_f32_e32 v62, v62
	v_fmamk_f32 v66, v66, 0x3e000000, v157
	v_fmamk_f32 v67, v67, 0x3e000000, v157
	v_mul_f32_e32 v51, v51, v50
	v_fmamk_f32 v50, v55, 0x3e000000, v157
	v_rcp_f32_e32 v66, v66
	v_rcp_f32_e32 v67, v67
	v_rcp_f32_e32 v50, v50
	v_fmamk_f32 v55, v62, 0x3e000000, v157
	v_rcp_f32_e32 v55, v55
	v_mul_f32_e32 v52, v56, v52
	v_mul_f32_e32 v58, v66, v58
	v_mul_f32_e32 v59, v67, v59
	v_mul_f32_e32 v52, v50, v52
	v_mul_f32_e32 v50, v57, v53
	v_mul_f32_e32 v53, v55, v50
	v_med3_f32 v55, v58, s44, v158
	v_med3_f32 v56, v59, s44, v158
	v_mov_b32_e32 v50, 0
	v_med3_f32 v54, v54, s44, v158
	v_med3_f32 v57, v51, s44, v158
	v_mov_b32_e32 v51, 0
	v_cvt_pk_fp8_f32 v50, v55, v56
	v_cvt_pk_fp8_f32 v51, v54, v57
	v_med3_f32 v55, v60, s44, v158
	v_med3_f32 v56, v61, s44, v158
	v_med3_f32 v52, v52, s44, v158
	v_med3_f32 v53, v53, s44, v158
	v_cvt_pk_fp8_f32 v50, v55, v56 op_sel:[0,0,1]
	v_cvt_pk_fp8_f32 v51, v52, v53 op_sel:[0,0,1]
	v_add_u32_e32 v68, 0x80, v159
	v_mad_i64_i32 v[52:53], s[24:25], v68, s43, v[150:151]
	v_lshl_add_u64 v[52:53], v[52:53], 0, v[148:149]
	global_store_dwordx2 v[52:53], v[50:51], off nt
	v_mul_f32_e32 v50, 0xbfb8aa3b, v46
	v_mul_f32_e32 v51, 0xbfb8aa3b, v47
	v_mul_f32_e32 v42, v46, v42
	v_mul_f32_e32 v43, v47, v43
	v_mul_f32_e32 v46, 0xbfb8aa3b, v48
	v_mul_f32_e32 v47, 0xbfb8aa3b, v49
	v_exp_f32_e32 v46, v46
	v_exp_f32_e32 v47, v47
	v_mul_f32_e32 v44, v48, v44
	v_mul_f32_e32 v48, 0xbfb8aa3b, v38
;     __device__ __forceinline__ void operator()(const f32x4 (&acc)[2][2][4][2], const pg8::Unit& u, int wr, int wc, int fr, int fq) const {
;     ...
;             for (int m = 0; m < 4; ++m) {
;                 unsigned char* rowp = O + (size_t)(row0 + ai * 128 + m * 16) * DFF + col0;
;                 float v[8];
; #pragma unroll
;                 for (int n = 0; n < 2; ++n)
; #pragma unroll
;                     for (int j = 0; j < 4; ++j) { const float g = acc[ai][0][m][n][j], up = acc[ai][1][m][n][j]; v[4 * n + j] = g * up * __builtin_amdgcn_rcpf(__builtin_fmaf(__builtin_amdgcn_exp2f(-1.44269504089f * g), 1.0f / ACT8_SCALE, 1.0f / ACT8_SCALE)); }
;                 u32x2 w; w.x = pk4_fp8(v[0], v[1], v[2], v[3]); w.y = pk4_fp8(v[4], v[5], v[6], v[7]);
;                 *(u32x2*)rowp = w;
	v_fmamk_f32 v46, v46, 0x3e000000, v157
	v_fmamk_f32 v47, v47, 0x3e000000, v157
	v_rcp_f32_e32 v46, v46
	v_rcp_f32_e32 v47, v47
	v_exp_f32_e32 v48, v48
	v_mul_f32_e32 v45, v49, v45
	v_mul_f32_e32 v44, v46, v44
	v_mul_f32_e32 v45, v47, v45
	v_fmamk_f32 v46, v48, 0x3e000000, v157
	v_mul_f32_e32 v47, 0xbfb8aa3b, v39
	v_rcp_f32_e32 v46, v46
	v_exp_f32_e32 v47, v47
	v_mul_f32_e32 v34, v38, v34
	v_exp_f32_e32 v50, v50
	v_mul_f32_e32 v38, v46, v34
	v_mul_f32_e32 v34, v39, v35
	v_fmamk_f32 v35, v47, 0x3e000000, v157
	v_mul_f32_e32 v39, 0xbfb8aa3b, v40
	v_exp_f32_e32 v51, v51
	v_rcp_f32_e32 v35, v35
	v_exp_f32_e32 v39, v39
	v_mul_f32_e32 v46, 0xbfb8aa3b, v41
	v_exp_f32_e32 v46, v46
	v_fmamk_f32 v50, v50, 0x3e000000, v157
	v_fmamk_f32 v51, v51, 0x3e000000, v157
	v_mul_f32_e32 v35, v35, v34
	v_fmamk_f32 v34, v39, 0x3e000000, v157
	v_rcp_f32_e32 v50, v50
	v_rcp_f32_e32 v51, v51
	v_rcp_f32_e32 v34, v34
	v_fmamk_f32 v39, v46, 0x3e000000, v157
	v_rcp_f32_e32 v39, v39
	v_mul_f32_e32 v36, v40, v36
	v_mul_f32_e32 v42, v50, v42
	v_mul_f32_e32 v43, v51, v43
	v_mul_f32_e32 v36, v34, v36
	v_mul_f32_e32 v34, v41, v37
	v_mul_f32_e32 v37, v39, v34
	v_med3_f32 v39, v42, s44, v158
	v_med3_f32 v40, v43, s44, v158
	v_mov_b32_e32 v34, 0
	v_med3_f32 v38, v38, s44, v158
	v_med3_f32 v41, v35, s44, v158
	v_mov_b32_e32 v35, 0
	v_cvt_pk_fp8_f32 v34, v39, v40
	v_cvt_pk_fp8_f32 v35, v38, v41
	v_med3_f32 v39, v44, s44, v158
	v_med3_f32 v40, v45, s44, v158
	v_med3_f32 v36, v36, s44, v158
	v_med3_f32 v37, v37, s44, v158
	v_cvt_pk_fp8_f32 v34, v39, v40 op_sel:[0,0,1]
	v_cvt_pk_fp8_f32 v35, v36, v37 op_sel:[0,0,1]
	v_add_u32_e32 v52, 0x90, v159
	v_mad_i64_i32 v[36:37], s[24:25], v52, s43, v[150:151]
	v_lshl_add_u64 v[36:37], v[36:37], 0, v[148:149]
	global_store_dwordx2 v[36:37], v[34:35], off nt
	v_mul_f32_e32 v34, 0xbfb8aa3b, v30
	v_mul_f32_e32 v35, 0xbfb8aa3b, v31
	v_mul_f32_e32 v26, v30, v26
	v_mul_f32_e32 v27, v31, v27
	v_mul_f32_e32 v30, 0xbfb8aa3b, v32
	v_mul_f32_e32 v31, 0xbfb8aa3b, v33
	v_exp_f32_e32 v30, v30
	v_exp_f32_e32 v31, v31
	v_mul_f32_e32 v28, v32, v28
	v_mul_f32_e32 v32, 0xbfb8aa3b, v22
	v_fmamk_f32 v30, v30, 0x3e000000, v157
	v_fmamk_f32 v31, v31, 0x3e000000, v157
	v_rcp_f32_e32 v30, v30
	v_rcp_f32_e32 v31, v31
	v_exp_f32_e32 v32, v32
	v_mul_f32_e32 v29, v33, v29
	v_mul_f32_e32 v28, v30, v28
	v_mul_f32_e32 v29, v31, v29
	v_fmamk_f32 v30, v32, 0x3e000000, v157
	v_mul_f32_e32 v31, 0xbfb8aa3b, v23
	v_rcp_f32_e32 v30, v30
	v_exp_f32_e32 v31, v31
	v_mul_f32_e32 v18, v22, v18
	v_exp_f32_e32 v34, v34
	v_mul_f32_e32 v22, v30, v18
	v_mul_f32_e32 v18, v23, v19
	v_fmamk_f32 v19, v31, 0x3e000000, v157
	v_mul_f32_e32 v23, 0xbfb8aa3b, v24
	v_exp_f32_e32 v35, v35
	v_rcp_f32_e32 v19, v19
	v_exp_f32_e32 v23, v23
	v_mul_f32_e32 v30, 0xbfb8aa3b, v25
	v_exp_f32_e32 v30, v30
	v_fmamk_f32 v34, v34, 0x3e000000, v157
	v_fmamk_f32 v35, v35, 0x3e000000, v157
	v_mul_f32_e32 v19, v19, v18
	v_fmamk_f32 v18, v23, 0x3e000000, v157
	v_rcp_f32_e32 v34, v34
	v_rcp_f32_e32 v35, v35
	v_rcp_f32_e32 v18, v18
	v_fmamk_f32 v23, v30, 0x3e000000, v157
	v_rcp_f32_e32 v23, v23
	v_mul_f32_e32 v20, v24, v20
	v_mul_f32_e32 v26, v34, v26
	v_mul_f32_e32 v27, v35, v27
	v_mul_f32_e32 v20, v18, v20
	v_mul_f32_e32 v18, v25, v21
	v_mul_f32_e32 v21, v23, v18
	v_med3_f32 v23, v26, s44, v158
	v_med3_f32 v24, v27, s44, v158
	v_mov_b32_e32 v18, 0
	v_med3_f32 v22, v22, s44, v158
	v_med3_f32 v25, v19, s44, v158
	v_mov_b32_e32 v19, 0
	v_cvt_pk_fp8_f32 v18, v23, v24
	v_cvt_pk_fp8_f32 v19, v22, v25
	v_med3_f32 v23, v28, s44, v158
	v_med3_f32 v24, v29, s44, v158
	v_med3_f32 v20, v20, s44, v158
	v_med3_f32 v21, v21, s44, v158
	v_cvt_pk_fp8_f32 v18, v23, v24 op_sel:[0,0,1]
	v_cvt_pk_fp8_f32 v19, v20, v21 op_sel:[0,0,1]
	v_add_u32_e32 v36, 0xa0, v159
	v_mad_i64_i32 v[20:21], s[24:25], v36, s43, v[150:151]
	v_lshl_add_u64 v[20:21], v[20:21], 0, v[148:149]
	global_store_dwordx2 v[20:21], v[18:19], off nt
	v_mul_f32_e32 v18, 0xbfb8aa3b, v14
	v_mul_f32_e32 v19, 0xbfb8aa3b, v15
	v_mul_f32_e32 v10, v14, v10
	v_mul_f32_e32 v11, v15, v11
	v_mul_f32_e32 v14, 0xbfb8aa3b, v16
	v_mul_f32_e32 v15, 0xbfb8aa3b, v17
	v_exp_f32_e32 v14, v14
	v_exp_f32_e32 v15, v15
	v_mul_f32_e32 v12, v16, v12
	v_mul_f32_e32 v16, 0xbfb8aa3b, v6
	v_fmamk_f32 v14, v14, 0x3e000000, v157
	v_fmamk_f32 v15, v15, 0x3e000000, v157
	v_rcp_f32_e32 v14, v14
	v_rcp_f32_e32 v15, v15
	v_exp_f32_e32 v16, v16
	v_mul_f32_e32 v13, v17, v13
	v_mul_f32_e32 v12, v14, v12
	v_mul_f32_e32 v13, v15, v13
	v_fmamk_f32 v14, v16, 0x3e000000, v157
	v_mul_f32_e32 v15, 0xbfb8aa3b, v7
	v_rcp_f32_e32 v14, v14
	v_exp_f32_e32 v15, v15
	v_mul_f32_e32 v2, v6, v2
	v_exp_f32_e32 v18, v18
	v_mul_f32_e32 v6, v14, v2
	v_mul_f32_e32 v2, v7, v3
	v_fmamk_f32 v3, v15, 0x3e000000, v157
	v_mul_f32_e32 v7, 0xbfb8aa3b, v8
	v_exp_f32_e32 v19, v19
	v_rcp_f32_e32 v3, v3
	v_exp_f32_e32 v7, v7
	v_mul_f32_e32 v14, 0xbfb8aa3b, v9
	v_exp_f32_e32 v14, v14
	v_fmamk_f32 v18, v18, 0x3e000000, v157
	v_fmamk_f32 v19, v19, 0x3e000000, v157
	v_mul_f32_e32 v3, v3, v2
	v_fmamk_f32 v2, v7, 0x3e000000, v157
	v_rcp_f32_e32 v18, v18
	v_rcp_f32_e32 v19, v19
	v_rcp_f32_e32 v2, v2
	v_fmamk_f32 v7, v14, 0x3e000000, v157
	v_rcp_f32_e32 v7, v7
	v_mul_f32_e32 v4, v8, v4
	v_mul_f32_e32 v10, v18, v10
	v_mul_f32_e32 v11, v19, v11
	v_mul_f32_e32 v4, v2, v4
	v_mul_f32_e32 v2, v9, v5
	v_mul_f32_e32 v5, v7, v2
	v_med3_f32 v7, v10, s44, v158
	v_med3_f32 v8, v11, s44, v158
	v_mov_b32_e32 v2, 0
	v_med3_f32 v6, v6, s44, v158
	v_med3_f32 v9, v3, s44, v158
	v_mov_b32_e32 v3, 0
	v_cvt_pk_fp8_f32 v2, v7, v8
	v_cvt_pk_fp8_f32 v3, v6, v9
	v_med3_f32 v7, v12, s44, v158
	v_med3_f32 v8, v13, s44, v158
	v_med3_f32 v4, v4, s44, v158
	v_med3_f32 v5, v5, s44, v158
	v_cvt_pk_fp8_f32 v2, v7, v8 op_sel:[0,0,1]
	v_cvt_pk_fp8_f32 v3, v4, v5 op_sel:[0,0,1]
	v_add_u32_e32 v20, 0xb0, v159
	v_mad_i64_i32 v[4:5], s[24:25], v20, s43, v[150:151]
	v_lshl_add_u64 v[4:5], v[4:5], 0, v[148:149]
	s_andn2_b64 vcc, exec, s[0:1]
	s_mov_b64 s[0:1], -1
	global_store_dwordx2 v[4:5], v[2:3], off nt
	s_cbranch_vccnz .LBB0_1444
	s_andn2_b64 vcc, exec, s[2:3]
	s_cbranch_vccnz .LBB0_1443
	s_barrier
	s_branch .LBB0_1443

;     __device__ __forceinline__ void operator()(const f32x4 (&acc)[2][2][4][2], const pg8::Unit& u, int wr, int wc, int fr, int fq) const {
;         const int row0 = u.pm * 256 + wr * 64 + fr, col0 = u.pn * 128 + wc * 32 + 8 * fq;
; #pragma unroll
;         for (int ai = 0; ai < 2; ++ai)
; #pragma unroll
;             for (int m = 0; m < 4; ++m) {
;                 unsigned char* rowp = O + (size_t)(row0 + ai * 128 + m * 16) * DFF + col0;
;                 float v[8];
; #pragma unroll
;                 for (int n = 0; n < 2; ++n)
; #pragma unroll
;                     for (int j = 0; j < 4; ++j) { const float g = acc[ai][0][m][n][j], up = acc[ai][1][m][n][j]; v[4 * n + j] = g * up * __builtin_amdgcn_rcpf(__builtin_fmaf(__builtin_amdgcn_exp2f(-1.44269504089f * g), 1.0f / ACT8_SCALE, 1.0f / ACT8_SCALE)); }
;                 u32x2 w; w.x = pk4_fp8(v[0], v[1], v[2], v[3]); w.y = pk4_fp8(v[4], v[5], v[6], v[7]);
;                 *(u32x2*)rowp = w;
.LBB0_2436:
	v_mul_f32_e32 v148, 0xbfb8aa3b, v126
	v_exp_f32_e32 v158, v148
	v_mul_f32_e32 v148, 0xbfb8aa3b, v127
	v_mul_f32_e32 v122, v126, v122
	v_mul_f32_e32 v123, v127, v123
	v_mul_f32_e32 v126, 0xbfb8aa3b, v128
	v_mul_f32_e32 v127, 0xbfb8aa3b, v129
	v_exp_f32_e32 v126, v126
	v_exp_f32_e32 v127, v127
	v_mul_f32_e32 v124, v128, v124
	v_mul_f32_e32 v128, 0xbfb8aa3b, v118
	v_fmamk_f32 v126, v126, 0x3e000000, v155
	v_fmamk_f32 v127, v127, 0x3e000000, v155
	v_rcp_f32_e32 v126, v126
	v_rcp_f32_e32 v127, v127
	v_exp_f32_e32 v128, v128
	v_mul_f32_e32 v125, v129, v125
	v_mul_f32_e32 v124, v126, v124
	v_mul_f32_e32 v125, v127, v125
	v_fmamk_f32 v126, v128, 0x3e000000, v155
	v_mul_f32_e32 v127, 0xbfb8aa3b, v119
	v_rcp_f32_e32 v126, v126
	v_exp_f32_e32 v127, v127
	v_mul_f32_e32 v114, v118, v114
	v_exp_f32_e32 v159, v148
	v_mul_f32_e32 v118, v126, v114
	v_mul_f32_e32 v114, v119, v115
	v_fmamk_f32 v115, v127, 0x3e000000, v155
	v_mul_f32_e32 v119, 0xbfb8aa3b, v120
	v_rcp_f32_e32 v115, v115
	v_exp_f32_e32 v119, v119
	v_mul_f32_e32 v126, 0xbfb8aa3b, v121
	v_exp_f32_e32 v126, v126
	v_fmamk_f32 v158, v158, 0x3e000000, v155
	v_fmamk_f32 v159, v159, 0x3e000000, v155
	v_mul_f32_e32 v115, v115, v114
	v_fmamk_f32 v114, v119, 0x3e000000, v155
	v_rcp_f32_e32 v158, v158
	v_rcp_f32_e32 v159, v159
	v_rcp_f32_e32 v114, v114
	v_fmamk_f32 v119, v126, 0x3e000000, v155
	v_rcp_f32_e32 v119, v119
	v_mul_f32_e32 v116, v120, v116
	v_mul_f32_e32 v122, v158, v122
	v_mul_f32_e32 v123, v159, v123
	v_mul_f32_e32 v116, v114, v116
	v_mul_f32_e32 v114, v121, v117
	v_mul_f32_e32 v117, v119, v114
	v_med3_f32 v119, v122, s42, v156
	v_med3_f32 v120, v123, s42, v156
	v_mov_b32_e32 v114, 0
	v_med3_f32 v118, v118, s42, v156
	v_med3_f32 v121, v115, s42, v156
	v_mov_b32_e32 v115, 0
	v_cvt_pk_fp8_f32 v114, v119, v120
	v_cvt_pk_fp8_f32 v115, v118, v121
	v_readlane_b32 s20, v253, 50
	v_med3_f32 v119, v124, s42, v156
	v_med3_f32 v120, v125, s42, v156
	v_med3_f32 v116, v116, s42, v156
	v_med3_f32 v117, v117, s42, v156
	v_readlane_b32 s21, v253, 51
	v_cvt_pk_fp8_f32 v114, v119, v120 op_sel:[0,0,1]
	v_cvt_pk_fp8_f32 v115, v116, v117 op_sel:[0,0,1]
	v_lshl_add_u32 v157, s18, 8, v1
	v_lshl_or_b32 v146, s43, 7, v151
	v_mov_b64_e32 v[148:149], s[20:21]
	v_ashrrev_i32_e32 v147, 31, v146
	v_mad_i64_i32 v[116:117], s[20:21], v157, s41, v[148:149]
	v_lshl_add_u64 v[116:117], v[116:117], 0, v[146:147]
	global_store_dwordx2 v[116:117], v[114:115], off nt
	v_mul_f32_e32 v114, 0xbfb8aa3b, v110
	v_mul_f32_e32 v115, 0xbfb8aa3b, v111
	v_mul_f32_e32 v106, v110, v106
	v_mul_f32_e32 v107, v111, v107
	v_mul_f32_e32 v110, 0xbfb8aa3b, v112
	v_mul_f32_e32 v111, 0xbfb8aa3b, v113
	v_exp_f32_e32 v110, v110
	v_exp_f32_e32 v111, v111
	v_mul_f32_e32 v108, v112, v108
	v_mul_f32_e32 v112, 0xbfb8aa3b, v102
	v_fmamk_f32 v110, v110, 0x3e000000, v155
	v_fmamk_f32 v111, v111, 0x3e000000, v155
	v_rcp_f32_e32 v110, v110
	v_rcp_f32_e32 v111, v111
	v_exp_f32_e32 v112, v112
	v_mul_f32_e32 v109, v113, v109
	v_mul_f32_e32 v108, v110, v108
	v_mul_f32_e32 v109, v111, v109
	v_fmamk_f32 v110, v112, 0x3e000000, v155
	v_mul_f32_e32 v111, 0xbfb8aa3b, v103
	v_rcp_f32_e32 v110, v110
	v_exp_f32_e32 v111, v111
	v_mul_f32_e32 v98, v102, v98
	v_exp_f32_e32 v114, v114
	v_mul_f32_e32 v102, v110, v98
	v_mul_f32_e32 v98, v103, v99
	v_fmamk_f32 v99, v111, 0x3e000000, v155
	v_mul_f32_e32 v103, 0xbfb8aa3b, v104
	v_exp_f32_e32 v115, v115
	v_rcp_f32_e32 v99, v99
	v_exp_f32_e32 v103, v103
	v_mul_f32_e32 v110, 0xbfb8aa3b, v105
	v_exp_f32_e32 v110, v110
	v_fmamk_f32 v114, v114, 0x3e000000, v155
	v_fmamk_f32 v115, v115, 0x3e000000, v155
	v_mul_f32_e32 v99, v99, v98
	v_fmamk_f32 v98, v103, 0x3e000000, v155
	v_rcp_f32_e32 v114, v114
	v_rcp_f32_e32 v115, v115
	v_rcp_f32_e32 v98, v98
	v_fmamk_f32 v103, v110, 0x3e000000, v155
	v_rcp_f32_e32 v103, v103
	v_mul_f32_e32 v100, v104, v100
	v_mul_f32_e32 v106, v114, v106
	v_mul_f32_e32 v107, v115, v107
	v_mul_f32_e32 v100, v98, v100
	v_mul_f32_e32 v98, v105, v101
	v_mul_f32_e32 v101, v103, v98
	v_med3_f32 v103, v106, s42, v156
	v_med3_f32 v104, v107, s42, v156
	v_mov_b32_e32 v98, 0
	v_med3_f32 v102, v102, s42, v156
	v_med3_f32 v105, v99, s42, v156
	v_mov_b32_e32 v99, 0
	v_cvt_pk_fp8_f32 v98, v103, v104
	v_cvt_pk_fp8_f32 v99, v102, v105
	v_med3_f32 v103, v108, s42, v156
	v_med3_f32 v104, v109, s42, v156
	v_med3_f32 v100, v100, s42, v156
	v_med3_f32 v101, v101, s42, v156
	v_cvt_pk_fp8_f32 v98, v103, v104 op_sel:[0,0,1]
	v_cvt_pk_fp8_f32 v99, v100, v101 op_sel:[0,0,1]
	v_or_b32_e32 v116, 16, v157
	v_mad_i64_i32 v[100:101], s[20:21], v116, s41, v[148:149]
	v_lshl_add_u64 v[100:101], v[100:101], 0, v[146:147]
	global_store_dwordx2 v[100:101], v[98:99], off nt
	v_mul_f32_e32 v98, 0xbfb8aa3b, v94
	v_mul_f32_e32 v99, 0xbfb8aa3b, v95
	v_mul_f32_e32 v90, v94, v90
	v_mul_f32_e32 v91, v95, v91
	v_mul_f32_e32 v94, 0xbfb8aa3b, v96
	v_mul_f32_e32 v95, 0xbfb8aa3b, v97
	v_exp_f32_e32 v94, v94
	v_exp_f32_e32 v95, v95
	v_mul_f32_e32 v92, v96, v92
	v_mul_f32_e32 v96, 0xbfb8aa3b, v86
	v_fmamk_f32 v94, v94, 0x3e000000, v155
	v_fmamk_f32 v95, v95, 0x3e000000, v155
	v_rcp_f32_e32 v94, v94
	v_rcp_f32_e32 v95, v95
	v_exp_f32_e32 v96, v96
	v_mul_f32_e32 v93, v97, v93
	v_mul_f32_e32 v92, v94, v92
	v_mul_f32_e32 v93, v95, v93
	v_fmamk_f32 v94, v96, 0x3e000000, v155
	v_mul_f32_e32 v95, 0xbfb8aa3b, v87
	v_rcp_f32_e32 v94, v94
	v_exp_f32_e32 v95, v95
	v_mul_f32_e32 v82, v86, v82
	v_exp_f32_e32 v98, v98
	v_mul_f32_e32 v86, v94, v82
	v_mul_f32_e32 v82, v87, v83
	v_fmamk_f32 v83, v95, 0x3e000000, v155
	v_mul_f32_e32 v87, 0xbfb8aa3b, v88
	v_exp_f32_e32 v99, v99
	v_rcp_f32_e32 v83, v83
	v_exp_f32_e32 v87, v87
	v_mul_f32_e32 v94, 0xbfb8aa3b, v89
;     __device__ __forceinline__ void operator()(const f32x4 (&acc)[2][2][4][2], const pg8::Unit& u, int wr, int wc, int fr, int fq) const {
;     ...
;             for (int m = 0; m < 4; ++m) {
;                 unsigned char* rowp = O + (size_t)(row0 + ai * 128 + m * 16) * DFF + col0;
;                 float v[8];
; #pragma unroll
;                 for (int n = 0; n < 2; ++n)
; #pragma unroll
;                     for (int j = 0; j < 4; ++j) { const float g = acc[ai][0][m][n][j], up = acc[ai][1][m][n][j]; v[4 * n + j] = g * up * __builtin_amdgcn_rcpf(__builtin_fmaf(__builtin_amdgcn_exp2f(-1.44269504089f * g), 1.0f / ACT8_SCALE, 1.0f / ACT8_SCALE)); }
;                 u32x2 w; w.x = pk4_fp8(v[0], v[1], v[2], v[3]); w.y = pk4_fp8(v[4], v[5], v[6], v[7]);
;                 *(u32x2*)rowp = w;
	v_exp_f32_e32 v94, v94
	v_fmamk_f32 v98, v98, 0x3e000000, v155
	v_fmamk_f32 v99, v99, 0x3e000000, v155
	v_mul_f32_e32 v83, v83, v82
	v_fmamk_f32 v82, v87, 0x3e000000, v155
	v_rcp_f32_e32 v98, v98
	v_rcp_f32_e32 v99, v99
	v_rcp_f32_e32 v82, v82
	v_fmamk_f32 v87, v94, 0x3e000000, v155
	v_rcp_f32_e32 v87, v87
	v_mul_f32_e32 v84, v88, v84
	v_mul_f32_e32 v90, v98, v90
	v_mul_f32_e32 v91, v99, v91
	v_mul_f32_e32 v84, v82, v84
	v_mul_f32_e32 v82, v89, v85
	v_mul_f32_e32 v85, v87, v82
	v_med3_f32 v87, v90, s42, v156
	v_med3_f32 v88, v91, s42, v156
	v_mov_b32_e32 v82, 0
	v_med3_f32 v86, v86, s42, v156
	v_med3_f32 v89, v83, s42, v156
	v_mov_b32_e32 v83, 0
	v_cvt_pk_fp8_f32 v82, v87, v88
	v_cvt_pk_fp8_f32 v83, v86, v89
	v_med3_f32 v87, v92, s42, v156
	v_med3_f32 v88, v93, s42, v156
	v_med3_f32 v84, v84, s42, v156
	v_med3_f32 v85, v85, s42, v156
	v_cvt_pk_fp8_f32 v82, v87, v88 op_sel:[0,0,1]
	v_cvt_pk_fp8_f32 v83, v84, v85 op_sel:[0,0,1]
	v_or_b32_e32 v100, 32, v157
	v_mad_i64_i32 v[84:85], s[20:21], v100, s41, v[148:149]
	v_lshl_add_u64 v[84:85], v[84:85], 0, v[146:147]
	global_store_dwordx2 v[84:85], v[82:83], off nt
	v_mul_f32_e32 v82, 0xbfb8aa3b, v78
	v_mul_f32_e32 v83, 0xbfb8aa3b, v79
	v_mul_f32_e32 v74, v78, v74
	v_mul_f32_e32 v75, v79, v75
	v_mul_f32_e32 v78, 0xbfb8aa3b, v80
	v_mul_f32_e32 v79, 0xbfb8aa3b, v81
	v_exp_f32_e32 v78, v78
	v_exp_f32_e32 v79, v79
	v_mul_f32_e32 v76, v80, v76
	v_mul_f32_e32 v80, 0xbfb8aa3b, v70
	v_fmamk_f32 v78, v78, 0x3e000000, v155
	v_fmamk_f32 v79, v79, 0x3e000000, v155
	v_rcp_f32_e32 v78, v78
	v_rcp_f32_e32 v79, v79
	v_exp_f32_e32 v80, v80
	v_mul_f32_e32 v77, v81, v77
	v_mul_f32_e32 v76, v78, v76
	v_mul_f32_e32 v77, v79, v77
	v_fmamk_f32 v78, v80, 0x3e000000, v155
	v_mul_f32_e32 v79, 0xbfb8aa3b, v71
	v_rcp_f32_e32 v78, v78
	v_exp_f32_e32 v79, v79
	v_mul_f32_e32 v66, v70, v66
	v_exp_f32_e32 v82, v82
	v_mul_f32_e32 v70, v78, v66
	v_mul_f32_e32 v66, v71, v67
	v_fmamk_f32 v67, v79, 0x3e000000, v155
	v_mul_f32_e32 v71, 0xbfb8aa3b, v72
	v_exp_f32_e32 v83, v83
	v_rcp_f32_e32 v67, v67
	v_exp_f32_e32 v71, v71
	v_mul_f32_e32 v78, 0xbfb8aa3b, v73
	v_exp_f32_e32 v78, v78
	v_fmamk_f32 v82, v82, 0x3e000000, v155
	v_fmamk_f32 v83, v83, 0x3e000000, v155
	v_mul_f32_e32 v67, v67, v66
	v_fmamk_f32 v66, v71, 0x3e000000, v155
	v_rcp_f32_e32 v82, v82
	v_rcp_f32_e32 v83, v83
	v_rcp_f32_e32 v66, v66
	v_fmamk_f32 v71, v78, 0x3e000000, v155
	v_rcp_f32_e32 v71, v71
	v_mul_f32_e32 v68, v72, v68
	v_mul_f32_e32 v74, v82, v74
	v_mul_f32_e32 v75, v83, v75
	v_mul_f32_e32 v68, v66, v68
	v_mul_f32_e32 v66, v73, v69
	v_mul_f32_e32 v69, v71, v66
	v_med3_f32 v71, v74, s42, v156
	v_med3_f32 v72, v75, s42, v156
	v_mov_b32_e32 v66, 0
	v_med3_f32 v70, v70, s42, v156
	v_med3_f32 v73, v67, s42, v156
	v_mov_b32_e32 v67, 0
	v_cvt_pk_fp8_f32 v66, v71, v72
	v_cvt_pk_fp8_f32 v67, v70, v73
	v_med3_f32 v71, v76, s42, v156
	v_med3_f32 v72, v77, s42, v156
	v_med3_f32 v68, v68, s42, v156
	v_med3_f32 v69, v69, s42, v156
	v_cvt_pk_fp8_f32 v66, v71, v72 op_sel:[0,0,1]
	v_cvt_pk_fp8_f32 v67, v68, v69 op_sel:[0,0,1]
	v_or_b32_e32 v84, 48, v157
	v_mad_i64_i32 v[68:69], s[20:21], v84, s41, v[148:149]
	v_lshl_add_u64 v[68:69], v[68:69], 0, v[146:147]
	global_store_dwordx2 v[68:69], v[66:67], off nt
	v_mul_f32_e32 v66, 0xbfb8aa3b, v62
	v_mul_f32_e32 v67, 0xbfb8aa3b, v63
	v_mul_f32_e32 v58, v62, v58
	v_mul_f32_e32 v59, v63, v59
	v_mul_f32_e32 v62, 0xbfb8aa3b, v64
	v_mul_f32_e32 v63, 0xbfb8aa3b, v65
	v_exp_f32_e32 v62, v62
	v_exp_f32_e32 v63, v63
	v_mul_f32_e32 v60, v64, v60
	v_mul_f32_e32 v64, 0xbfb8aa3b, v54
	v_fmamk_f32 v62, v62, 0x3e000000, v155
	v_fmamk_f32 v63, v63, 0x3e000000, v155
	v_rcp_f32_e32 v62, v62
	v_rcp_f32_e32 v63, v63
	v_exp_f32_e32 v64, v64
	v_mul_f32_e32 v61, v65, v61
	v_mul_f32_e32 v60, v62, v60
	v_mul_f32_e32 v61, v63, v61
	v_fmamk_f32 v62, v64, 0x3e000000, v155
	v_mul_f32_e32 v63, 0xbfb8aa3b, v55
	v_rcp_f32_e32 v62, v62
	v_exp_f32_e32 v63, v63
	v_mul_f32_e32 v50, v54, v50
	v_exp_f32_e32 v66, v66
	v_mul_f32_e32 v54, v62, v50
	v_mul_f32_e32 v50, v55, v51
	v_fmamk_f32 v51, v63, 0x3e000000, v155
	v_mul_f32_e32 v55, 0xbfb8aa3b, v56
	v_exp_f32_e32 v67, v67
	v_rcp_f32_e32 v51, v51
	v_exp_f32_e32 v55, v55
	v_mul_f32_e32 v62, 0xbfb8aa3b, v57
	v_exp_f32_e32 v62, v62
	v_fmamk_f32 v66, v66, 0x3e000000, v155
	v_fmamk_f32 v67, v67, 0x3e000000, v155
	v_mul_f32_e32 v51, v51, v50
	v_fmamk_f32 v50, v55, 0x3e000000, v155
	v_rcp_f32_e32 v66, v66
	v_rcp_f32_e32 v67, v67
	v_rcp_f32_e32 v50, v50
	v_fmamk_f32 v55, v62, 0x3e000000, v155
	v_rcp_f32_e32 v55, v55
	v_mul_f32_e32 v52, v56, v52
	v_mul_f32_e32 v58, v66, v58
	v_mul_f32_e32 v59, v67, v59
	v_mul_f32_e32 v52, v50, v52
	v_mul_f32_e32 v50, v57, v53
	v_mul_f32_e32 v53, v55, v50
	v_med3_f32 v55, v58, s42, v156
	v_med3_f32 v56, v59, s42, v156
	v_mov_b32_e32 v50, 0
	v_med3_f32 v54, v54, s42, v156
	v_med3_f32 v57, v51, s42, v156
	v_mov_b32_e32 v51, 0
	v_cvt_pk_fp8_f32 v50, v55, v56
	v_cvt_pk_fp8_f32 v51, v54, v57
	v_med3_f32 v55, v60, s42, v156
	v_med3_f32 v56, v61, s42, v156
	v_med3_f32 v52, v52, s42, v156
	v_med3_f32 v53, v53, s42, v156
	v_cvt_pk_fp8_f32 v50, v55, v56 op_sel:[0,0,1]
	v_cvt_pk_fp8_f32 v51, v52, v53 op_sel:[0,0,1]
	v_add_u32_e32 v68, 0x80, v157
	v_mad_i64_i32 v[52:53], s[20:21], v68, s41, v[148:149]
	v_lshl_add_u64 v[52:53], v[52:53], 0, v[146:147]
	global_store_dwordx2 v[52:53], v[50:51], off nt
	v_mul_f32_e32 v50, 0xbfb8aa3b, v46
	v_mul_f32_e32 v51, 0xbfb8aa3b, v47
	v_mul_f32_e32 v42, v46, v42
	v_mul_f32_e32 v43, v47, v43
	v_mul_f32_e32 v46, 0xbfb8aa3b, v48
	v_mul_f32_e32 v47, 0xbfb8aa3b, v49
	v_exp_f32_e32 v46, v46
	v_exp_f32_e32 v47, v47
	v_mul_f32_e32 v44, v48, v44
	v_mul_f32_e32 v48, 0xbfb8aa3b, v38
;     __device__ __forceinline__ void operator()(const f32x4 (&acc)[2][2][4][2], const pg8::Unit& u, int wr, int wc, int fr, int fq) const {
;     ...
;             for (int m = 0; m < 4; ++m) {
;                 unsigned char* rowp = O + (size_t)(row0 + ai * 128 + m * 16) * DFF + col0;
;                 float v[8];
; #pragma unroll
;                 for (int n = 0; n < 2; ++n)
; #pragma unroll
;                     for (int j = 0; j < 4; ++j) { const float g = acc[ai][0][m][n][j], up = acc[ai][1][m][n][j]; v[4 * n + j] = g * up * __builtin_amdgcn_rcpf(__builtin_fmaf(__builtin_amdgcn_exp2f(-1.44269504089f * g), 1.0f / ACT8_SCALE, 1.0f / ACT8_SCALE)); }
;                 u32x2 w; w.x = pk4_fp8(v[0], v[1], v[2], v[3]); w.y = pk4_fp8(v[4], v[5], v[6], v[7]);
;                 *(u32x2*)rowp = w;
	v_fmamk_f32 v46, v46, 0x3e000000, v155
	v_fmamk_f32 v47, v47, 0x3e000000, v155
	v_rcp_f32_e32 v46, v46
	v_rcp_f32_e32 v47, v47
	v_exp_f32_e32 v48, v48
	v_mul_f32_e32 v45, v49, v45
	v_mul_f32_e32 v44, v46, v44
	v_mul_f32_e32 v45, v47, v45
	v_fmamk_f32 v46, v48, 0x3e000000, v155
	v_mul_f32_e32 v47, 0xbfb8aa3b, v39
	v_rcp_f32_e32 v46, v46
	v_exp_f32_e32 v47, v47
	v_mul_f32_e32 v34, v38, v34
	v_exp_f32_e32 v50, v50
	v_mul_f32_e32 v38, v46, v34
	v_mul_f32_e32 v34, v39, v35
	v_fmamk_f32 v35, v47, 0x3e000000, v155
	v_mul_f32_e32 v39, 0xbfb8aa3b, v40
	v_exp_f32_e32 v51, v51
	v_rcp_f32_e32 v35, v35
	v_exp_f32_e32 v39, v39
	v_mul_f32_e32 v46, 0xbfb8aa3b, v41
	v_exp_f32_e32 v46, v46
	v_fmamk_f32 v50, v50, 0x3e000000, v155
	v_fmamk_f32 v51, v51, 0x3e000000, v155
	v_mul_f32_e32 v35, v35, v34
	v_fmamk_f32 v34, v39, 0x3e000000, v155
	v_rcp_f32_e32 v50, v50
	v_rcp_f32_e32 v51, v51
	v_rcp_f32_e32 v34, v34
	v_fmamk_f32 v39, v46, 0x3e000000, v155
	v_rcp_f32_e32 v39, v39
	v_mul_f32_e32 v36, v40, v36
	v_mul_f32_e32 v42, v50, v42
	v_mul_f32_e32 v43, v51, v43
	v_mul_f32_e32 v36, v34, v36
	v_mul_f32_e32 v34, v41, v37
	v_mul_f32_e32 v37, v39, v34
	v_med3_f32 v39, v42, s42, v156
	v_med3_f32 v40, v43, s42, v156
	v_mov_b32_e32 v34, 0
	v_med3_f32 v38, v38, s42, v156
	v_med3_f32 v41, v35, s42, v156
	v_mov_b32_e32 v35, 0
	v_cvt_pk_fp8_f32 v34, v39, v40
	v_cvt_pk_fp8_f32 v35, v38, v41
	v_med3_f32 v39, v44, s42, v156
	v_med3_f32 v40, v45, s42, v156
	v_med3_f32 v36, v36, s42, v156
	v_med3_f32 v37, v37, s42, v156
	v_cvt_pk_fp8_f32 v34, v39, v40 op_sel:[0,0,1]
	v_cvt_pk_fp8_f32 v35, v36, v37 op_sel:[0,0,1]
	v_add_u32_e32 v52, 0x90, v157
	v_mad_i64_i32 v[36:37], s[20:21], v52, s41, v[148:149]
	v_lshl_add_u64 v[36:37], v[36:37], 0, v[146:147]
	global_store_dwordx2 v[36:37], v[34:35], off nt
	v_mul_f32_e32 v34, 0xbfb8aa3b, v30
	v_mul_f32_e32 v35, 0xbfb8aa3b, v31
	v_mul_f32_e32 v26, v30, v26
	v_mul_f32_e32 v27, v31, v27
	v_mul_f32_e32 v30, 0xbfb8aa3b, v32
	v_mul_f32_e32 v31, 0xbfb8aa3b, v33
	v_exp_f32_e32 v30, v30
	v_exp_f32_e32 v31, v31
	v_mul_f32_e32 v28, v32, v28
	v_mul_f32_e32 v32, 0xbfb8aa3b, v22
	v_fmamk_f32 v30, v30, 0x3e000000, v155
	v_fmamk_f32 v31, v31, 0x3e000000, v155
	v_rcp_f32_e32 v30, v30
	v_rcp_f32_e32 v31, v31
	v_exp_f32_e32 v32, v32
	v_mul_f32_e32 v29, v33, v29
	v_mul_f32_e32 v28, v30, v28
	v_mul_f32_e32 v29, v31, v29
	v_fmamk_f32 v30, v32, 0x3e000000, v155
	v_mul_f32_e32 v31, 0xbfb8aa3b, v23
	v_rcp_f32_e32 v30, v30
	v_exp_f32_e32 v31, v31
	v_mul_f32_e32 v18, v22, v18
	v_exp_f32_e32 v34, v34
	v_mul_f32_e32 v22, v30, v18
	v_mul_f32_e32 v18, v23, v19
	v_fmamk_f32 v19, v31, 0x3e000000, v155
	v_mul_f32_e32 v23, 0xbfb8aa3b, v24
	v_exp_f32_e32 v35, v35
	v_rcp_f32_e32 v19, v19
	v_exp_f32_e32 v23, v23
	v_mul_f32_e32 v30, 0xbfb8aa3b, v25
	v_exp_f32_e32 v30, v30
	v_fmamk_f32 v34, v34, 0x3e000000, v155
	v_fmamk_f32 v35, v35, 0x3e000000, v155
	v_mul_f32_e32 v19, v19, v18
	v_fmamk_f32 v18, v23, 0x3e000000, v155
	v_rcp_f32_e32 v34, v34
	v_rcp_f32_e32 v35, v35
	v_rcp_f32_e32 v18, v18
	v_fmamk_f32 v23, v30, 0x3e000000, v155
	v_rcp_f32_e32 v23, v23
	v_mul_f32_e32 v20, v24, v20
	v_mul_f32_e32 v26, v34, v26
	v_mul_f32_e32 v27, v35, v27
	v_mul_f32_e32 v20, v18, v20
	v_mul_f32_e32 v18, v25, v21
	v_mul_f32_e32 v21, v23, v18
	v_med3_f32 v23, v26, s42, v156
	v_med3_f32 v24, v27, s42, v156
	v_mov_b32_e32 v18, 0
	v_med3_f32 v22, v22, s42, v156
	v_med3_f32 v25, v19, s42, v156
	v_mov_b32_e32 v19, 0
	v_cvt_pk_fp8_f32 v18, v23, v24
	v_cvt_pk_fp8_f32 v19, v22, v25
	v_med3_f32 v23, v28, s42, v156
	v_med3_f32 v24, v29, s42, v156
	v_med3_f32 v20, v20, s42, v156
	v_med3_f32 v21, v21, s42, v156
	v_cvt_pk_fp8_f32 v18, v23, v24 op_sel:[0,0,1]
	v_cvt_pk_fp8_f32 v19, v20, v21 op_sel:[0,0,1]
	v_add_u32_e32 v36, 0xa0, v157
	v_mad_i64_i32 v[20:21], s[20:21], v36, s41, v[148:149]
	v_lshl_add_u64 v[20:21], v[20:21], 0, v[146:147]
	global_store_dwordx2 v[20:21], v[18:19], off nt
	v_mul_f32_e32 v18, 0xbfb8aa3b, v14
	v_mul_f32_e32 v19, 0xbfb8aa3b, v15
	v_mul_f32_e32 v10, v14, v10
	v_mul_f32_e32 v11, v15, v11
	v_mul_f32_e32 v14, 0xbfb8aa3b, v16
	v_mul_f32_e32 v15, 0xbfb8aa3b, v17
	v_exp_f32_e32 v14, v14
	v_exp_f32_e32 v15, v15
	v_mul_f32_e32 v12, v16, v12
	v_mul_f32_e32 v16, 0xbfb8aa3b, v6
	v_fmamk_f32 v14, v14, 0x3e000000, v155
	v_fmamk_f32 v15, v15, 0x3e000000, v155
	v_rcp_f32_e32 v14, v14
	v_rcp_f32_e32 v15, v15
	v_exp_f32_e32 v16, v16
	v_mul_f32_e32 v13, v17, v13
	v_mul_f32_e32 v12, v14, v12
	v_mul_f32_e32 v13, v15, v13
	v_fmamk_f32 v14, v16, 0x3e000000, v155
	v_mul_f32_e32 v15, 0xbfb8aa3b, v7
	v_rcp_f32_e32 v14, v14
	v_exp_f32_e32 v15, v15
	v_mul_f32_e32 v2, v6, v2
	v_exp_f32_e32 v18, v18
	v_mul_f32_e32 v6, v14, v2
	v_mul_f32_e32 v2, v7, v3
	v_fmamk_f32 v3, v15, 0x3e000000, v155
	v_mul_f32_e32 v7, 0xbfb8aa3b, v8
	v_exp_f32_e32 v19, v19
	v_rcp_f32_e32 v3, v3
	v_exp_f32_e32 v7, v7
	v_mul_f32_e32 v14, 0xbfb8aa3b, v9
	v_exp_f32_e32 v14, v14
	v_fmamk_f32 v18, v18, 0x3e000000, v155
	v_fmamk_f32 v19, v19, 0x3e000000, v155
	v_mul_f32_e32 v3, v3, v2
	v_fmamk_f32 v2, v7, 0x3e000000, v155
	v_rcp_f32_e32 v18, v18
	v_rcp_f32_e32 v19, v19
	v_rcp_f32_e32 v2, v2
	v_fmamk_f32 v7, v14, 0x3e000000, v155
	v_rcp_f32_e32 v7, v7
	v_mul_f32_e32 v4, v8, v4
	v_mul_f32_e32 v10, v18, v10
	v_mul_f32_e32 v11, v19, v11
	v_mul_f32_e32 v4, v2, v4
	v_mul_f32_e32 v2, v9, v5
	v_mul_f32_e32 v5, v7, v2
	v_med3_f32 v7, v10, s42, v156
	v_med3_f32 v8, v11, s42, v156
	v_mov_b32_e32 v2, 0
	v_med3_f32 v6, v6, s42, v156
	v_med3_f32 v9, v3, s42, v156
	v_mov_b32_e32 v3, 0
	v_cvt_pk_fp8_f32 v2, v7, v8
	v_cvt_pk_fp8_f32 v3, v6, v9
	v_med3_f32 v7, v12, s42, v156
	v_med3_f32 v8, v13, s42, v156
	v_med3_f32 v4, v4, s42, v156
	v_med3_f32 v5, v5, s42, v156
	v_cvt_pk_fp8_f32 v2, v7, v8 op_sel:[0,0,1]
	v_cvt_pk_fp8_f32 v3, v4, v5 op_sel:[0,0,1]
	v_add_u32_e32 v20, 0xb0, v157
	v_mad_i64_i32 v[4:5], s[20:21], v20, s41, v[148:149]
	v_lshl_add_u64 v[4:5], v[4:5], 0, v[146:147]
	s_andn2_b64 vcc, exec, s[0:1]
	s_mov_b64 s[0:1], -1
	global_store_dwordx2 v[4:5], v[2:3], off nt
	s_cbranch_vccnz .LBB0_2429
	s_andn2_b64 vcc, exec, s[4:5]
	s_cbranch_vccnz .LBB0_2428
	s_barrier
	s_branch .LBB0_2428
